# touch-prefetch row-stats lines at top of FFN-in epilogue (L1/L2 warm) to shorten 8 serialized stats round trips
# speedup vs baseline: 1.0226x; 1.0226x over previous
; #define PG8_STAGE(bufoff, gbase, voff) do { _Pragma("unroll") for (int _i = 0; _i < 2; ++_i) \
;         __builtin_amdgcn_global_load_lds((const unsigned*)((const char*)(gbase) + (voff)[_i]), (LAS unsigned*)(lds + (bufoff) + ldsw + _i * 8192), 16, 0, 0); } while (0)
; #define PG8_LDA(dst, b, h) do { _Pragma("unroll") for (int m = 0; m < 4; ++m) _Pragma("unroll") for (int k = 0; k < 2; ++k) dst[m][k] = *(const LAS bf16x8*)(lds + PG8_SA(b, h) + aoff + m * 2048 + k * 1024); } while (0)
; #define PG8_WAIT_V(n) asm volatile("s_waitcnt vmcnt(" #n ")" ::: "memory")
; #define PG8_WAIT_L(n) asm volatile("s_waitcnt lgkmcnt(" #n ")" ::: "memory")
; template <class Epi>
; __device__ __forceinline__ void gemm_phase(LAS unsigned char* lds, const Gemm g, const StaticOrder& S, const Epi& E) {
;     ...
;         for (int t = 0; t < nt; t += 2) {
;             const bool last = (t == nt - 2);
;             const char* a1 = cA + (size_t)(t + 1) * kstep;
;             const char* a2 = last ? nA : cA + (size_t)(t + 2) * kstep; const char* b2 = last ? nB : cB + (size_t)(t + 2) * kstep;
;             const char* a3 = a2 + kstep; const char* b3 = b2 + kstep;
;             PG8_LDB(B0, 0, 0); PG8_SCHED; PG8_LDA(At, 0, 0); PG8_STAGE(PG8_SA(1, 1), a1 + hstep, voffA);
;             PG8_WAIT_L(8); PG8_BAR; PG8_WAIT_L(0); PG8_MMA(0, 0, At, B0); PG8_BAR; PG8_SCHED;
;             PG8_LDB(B1, 0, 1); PG8_STAGE(PG8_SB(0, 0), b2, voffB);
;             PG8_BAR; PG8_WAIT_L(0); PG8_MMA(0, 1, At, B1); PG8_BAR;
;             PG8_LDA(At, 0, 1); PG8_STAGE(PG8_SA(0, 0), a2, voffA);
;             PG8_BAR; PG8_WAIT_L(0); PG8_MMA(1, 0, At, B0); PG8_BAR; PG8_SCHED;
;             PG8_STAGE(PG8_SB(0, 1), b2 + hstep, voffB);
;             PG8_WAIT_V(6); PG8_BAR; PG8_MMA(1, 1, At, B1); PG8_BAR;
;             PG8_LDB(B0, 1, 0); PG8_SCHED; PG8_LDA(At, 1, 0); PG8_STAGE(PG8_SA(0, 1), a2 + hstep, voffA);
;             PG8_WAIT_L(8); PG8_BAR; PG8_WAIT_L(0); PG8_MMA(0, 0, At, B0); PG8_BAR; PG8_SCHED;
;             PG8_LDB(B1, 1, 1); PG8_STAGE(PG8_SB(1, 0), b3, voffB);
;             PG8_BAR; PG8_WAIT_L(0); PG8_MMA(0, 1, At, B1); PG8_BAR;
;             PG8_LDA(At, 1, 1); PG8_STAGE(PG8_SA(1, 0), a3, voffA);
;             PG8_BAR; PG8_WAIT_L(0); PG8_MMA(1, 0, At, B0); PG8_BAR; PG8_SCHED;
;             PG8_STAGE(PG8_SB(1, 1), b3 + hstep, voffB);
;             PG8_WAIT_V(6); PG8_BAR; PG8_MMA(1, 1, At, B1); PG8_BAR;
.LBB0_878:
	s_add_u32 s14, s10, 0xfffc0080
	s_addc_u32 s15, s11, -1
	s_add_i32 s60, 0, 0x10000
	v_add_u32_e32 v76, s60, v217
	ds_read_b128 v[60:63], v76
	ds_read_b128 v[64:67], v76 offset:1024
	ds_read_b128 v[72:75], v76 offset:2048
	ds_read_b128 v[76:79], v76 offset:3072
	s_cmp_eq_u32 s59, 12
	s_cselect_b32 s17, s39, s15
	s_cselect_b32 s16, s55, s14
	s_cselect_b32 s15, s1, s58
	s_cselect_b32 s14, s56, s57
	v_lshl_add_u64 v[188:189], s[10:11], 0, v[174:175]
	s_add_i32 m0, s26, 0xc000
	ds_read_b128 v[80:83], v223
	ds_read_b128 v[84:87], v223 offset:1024
	ds_read_b128 v[92:95], v223 offset:2048
	ds_read_b128 v[96:99], v223 offset:3072
	ds_read_b128 v[160:163], v223 offset:4096
	ds_read_b128 v[164:167], v223 offset:5120
	ds_read_b128 v[178:181], v223 offset:6144
	ds_read_b128 v[182:185], v223 offset:7168
	global_load_lds_dwordx4 v[188:189], off
	v_lshl_add_u64 v[188:189], s[10:11], 0, v[176:177]
	s_add_i32 m0, s26, 0xe000
	s_nop 0
	global_load_lds_dwordx4 v[188:189], off
	s_waitcnt lgkmcnt(8)
	s_barrier
	s_waitcnt lgkmcnt(0)
	s_setprio 1
	s_waitcnt lgkmcnt(0)
	v_mfma_f32_16x16x32_bf16 v[156:159], v[60:63], v[80:83], v[156:159]
	v_mfma_f32_16x16x32_bf16 v[148:151], v[72:75], v[80:83], v[148:151]
	v_mfma_f32_16x16x32_bf16 v[140:143], v[60:63], v[92:95], v[140:143]
	v_mfma_f32_16x16x32_bf16 v[132:135], v[72:75], v[92:95], v[132:135]
	v_mfma_f32_16x16x32_bf16 v[124:127], v[60:63], v[160:163], v[124:127]
	v_mfma_f32_16x16x32_bf16 v[116:119], v[72:75], v[160:163], v[116:119]
	v_mfma_f32_16x16x32_bf16 v[108:111], v[60:63], v[178:181], v[108:111]
	v_mfma_f32_16x16x32_bf16 v[100:103], v[72:75], v[178:181], v[100:103]
	v_mfma_f32_16x16x32_bf16 v[156:159], v[64:67], v[84:87], v[156:159]
	v_mfma_f32_16x16x32_bf16 v[148:151], v[76:79], v[84:87], v[148:151]
	v_mfma_f32_16x16x32_bf16 v[140:143], v[64:67], v[96:99], v[140:143]
	v_mfma_f32_16x16x32_bf16 v[132:135], v[76:79], v[96:99], v[132:135]
	v_mfma_f32_16x16x32_bf16 v[124:127], v[64:67], v[164:167], v[124:127]
	v_mfma_f32_16x16x32_bf16 v[116:119], v[76:79], v[164:167], v[116:119]
	v_mfma_f32_16x16x32_bf16 v[108:111], v[64:67], v[182:185], v[108:111]
	v_mfma_f32_16x16x32_bf16 v[100:103], v[76:79], v[182:185], v[100:103]
	s_setprio 0
	s_barrier
	s_add_i32 s62, 0, 0x14000
	s_add_i32 s60, s60, s21
	v_add_u32_e32 v186, s62, v217
	v_lshl_add_u64 v[188:189], s[14:15], 0, v[190:191]
	s_mov_b32 m0, s60
	ds_read_b128 v[194:197], v186
	ds_read_b128 v[198:201], v186 offset:1024
	ds_read_b128 v[204:207], v186 offset:2048
	ds_read_b128 v[208:211], v186 offset:3072
	global_load_lds_dwordx4 v[188:189], off
	v_lshl_add_u64 v[224:225], s[14:15], 0, v[168:169]
	s_add_i32 m0, s60, 0x2000
	s_nop 0
	global_load_lds_dwordx4 v[224:225], off
	s_barrier
	s_waitcnt lgkmcnt(0)
	s_setprio 1
	s_waitcnt lgkmcnt(0)
	v_mfma_f32_16x16x32_bf16 v[152:155], v[194:197], v[80:83], v[152:155]
	v_mfma_f32_16x16x32_bf16 v[80:83], v[204:207], v[80:83], v[144:147]
	v_mfma_f32_16x16x32_bf16 v[152:155], v[198:201], v[84:87], v[152:155]
	v_mfma_f32_16x16x32_bf16 v[80:83], v[208:211], v[84:87], v[80:83]
	v_mfma_f32_16x16x32_bf16 v[84:87], v[194:197], v[92:95], v[136:139]
	v_mfma_f32_16x16x32_bf16 v[92:95], v[204:207], v[92:95], v[128:131]
	v_mfma_f32_16x16x32_bf16 v[112:115], v[204:207], v[160:163], v[112:115]
	v_mfma_f32_16x16x32_bf16 v[104:107], v[194:197], v[178:181], v[104:107]
	v_mfma_f32_16x16x32_bf16 v[88:91], v[204:207], v[178:181], v[88:91]
	v_mfma_f32_16x16x32_bf16 v[84:87], v[198:201], v[96:99], v[84:87]
	v_mfma_f32_16x16x32_bf16 v[92:95], v[208:211], v[96:99], v[92:95]
	v_mfma_f32_16x16x32_bf16 v[96:99], v[194:197], v[160:163], v[120:123]
	v_mfma_f32_16x16x32_bf16 v[112:115], v[208:211], v[164:167], v[112:115]
	v_mfma_f32_16x16x32_bf16 v[104:107], v[198:201], v[182:185], v[104:107]
	v_mfma_f32_16x16x32_bf16 v[88:91], v[208:211], v[182:185], v[88:91]
	v_mfma_f32_16x16x32_bf16 v[96:99], v[198:201], v[164:167], v[96:99]
	s_setprio 0
	s_mov_b32 m0, s26
	v_lshl_add_u64 v[226:227], s[16:17], 0, v[172:173]
	s_barrier
	ds_read_b128 v[120:123], v223 offset:16384
	ds_read_b128 v[128:131], v223 offset:17408
	ds_read_b128 v[136:139], v223 offset:18432
	ds_read_b128 v[144:147], v223 offset:19456
	ds_read_b128 v[160:163], v223 offset:20480
	ds_read_b128 v[164:167], v223 offset:21504
	ds_read_b128 v[178:181], v223 offset:22528
	ds_read_b128 v[182:185], v223 offset:23552
	global_load_lds_dwordx4 v[226:227], off
	v_lshl_add_u64 v[240:241], s[16:17], 0, v[170:171]
	s_mov_b32 m0, s27
	s_nop 0
	global_load_lds_dwordx4 v[240:241], off
	s_barrier
	s_waitcnt lgkmcnt(0)
	s_setprio 1
	s_waitcnt lgkmcnt(0)
	v_mfma_f32_16x16x32_bf16 v[68:71], v[60:63], v[120:123], v[68:71]
	v_mfma_f32_16x16x32_bf16 v[52:55], v[72:75], v[120:123], v[52:55]
	v_mfma_f32_16x16x32_bf16 v[44:47], v[60:63], v[136:139], v[44:47]
	v_mfma_f32_16x16x32_bf16 v[36:39], v[72:75], v[136:139], v[36:39]
	v_mfma_f32_16x16x32_bf16 v[28:31], v[60:63], v[160:163], v[28:31]
	v_mfma_f32_16x16x32_bf16 v[20:23], v[72:75], v[160:163], v[20:23]
	v_mfma_f32_16x16x32_bf16 v[12:15], v[60:63], v[178:181], v[12:15]
	v_mfma_f32_16x16x32_bf16 v[4:7], v[72:75], v[178:181], v[4:7]
	v_mfma_f32_16x16x32_bf16 v[68:71], v[64:67], v[128:131], v[68:71]
	v_mfma_f32_16x16x32_bf16 v[52:55], v[76:79], v[128:131], v[52:55]
	v_mfma_f32_16x16x32_bf16 v[44:47], v[64:67], v[144:147], v[44:47]
	v_mfma_f32_16x16x32_bf16 v[36:39], v[76:79], v[144:147], v[36:39]
	v_mfma_f32_16x16x32_bf16 v[28:31], v[64:67], v[164:167], v[28:31]
	v_mfma_f32_16x16x32_bf16 v[20:23], v[76:79], v[164:167], v[20:23]
	v_mfma_f32_16x16x32_bf16 v[12:15], v[64:67], v[182:185], v[12:15]
	v_mfma_f32_16x16x32_bf16 v[4:7], v[76:79], v[182:185], v[4:7]
	s_setprio 0
	s_barrier
; #define PG8_STAGE(bufoff, gbase, voff) do { _Pragma("unroll") for (int _i = 0; _i < 2; ++_i) \
;         __builtin_amdgcn_global_load_lds((const unsigned*)((const char*)(gbase) + (voff)[_i]), (LAS unsigned*)(lds + (bufoff) + ldsw + _i * 8192), 16, 0, 0); } while (0)
; #define PG8_LDA(dst, b, h) do { _Pragma("unroll") for (int m = 0; m < 4; ++m) _Pragma("unroll") for (int k = 0; k < 2; ++k) dst[m][k] = *(const LAS bf16x8*)(lds + PG8_SA(b, h) + aoff + m * 2048 + k * 1024); } while (0)
; #define PG8_WAIT_V(n) asm volatile("s_waitcnt vmcnt(" #n ")" ::: "memory")
; #define PG8_WAIT_L(n) asm volatile("s_waitcnt lgkmcnt(" #n ")" ::: "memory")
; template <class Epi>
; __device__ __forceinline__ void gemm_phase(LAS unsigned char* lds, const Gemm g, const StaticOrder& S, const Epi& E) {
;     ...
;         for (int t = 0; t < nt; t += 2) {
;             const bool last = (t == nt - 2);
;             const char* a1 = cA + (size_t)(t + 1) * kstep;
;             const char* a2 = last ? nA : cA + (size_t)(t + 2) * kstep; const char* b2 = last ? nB : cB + (size_t)(t + 2) * kstep;
;             const char* a3 = a2 + kstep; const char* b3 = b2 + kstep;
;             PG8_LDB(B0, 0, 0); PG8_SCHED; PG8_LDA(At, 0, 0); PG8_STAGE(PG8_SA(1, 1), a1 + hstep, voffA);
;             PG8_WAIT_L(8); PG8_BAR; PG8_WAIT_L(0); PG8_MMA(0, 0, At, B0); PG8_BAR; PG8_SCHED;
;             PG8_LDB(B1, 0, 1); PG8_STAGE(PG8_SB(0, 0), b2, voffB);
;             PG8_BAR; PG8_WAIT_L(0); PG8_MMA(0, 1, At, B1); PG8_BAR;
;             PG8_LDA(At, 0, 1); PG8_STAGE(PG8_SA(0, 0), a2, voffA);
;             PG8_BAR; PG8_WAIT_L(0); PG8_MMA(1, 0, At, B0); PG8_BAR; PG8_SCHED;
;             PG8_STAGE(PG8_SB(0, 1), b2 + hstep, voffB);
;             PG8_WAIT_V(6); PG8_BAR; PG8_MMA(1, 1, At, B1); PG8_BAR;
;             PG8_LDB(B0, 1, 0); PG8_SCHED; PG8_LDA(At, 1, 0); PG8_STAGE(PG8_SA(0, 1), a2 + hstep, voffA);
;             PG8_WAIT_L(8); PG8_BAR; PG8_WAIT_L(0); PG8_MMA(0, 0, At, B0); PG8_BAR; PG8_SCHED;
;             PG8_LDB(B1, 1, 1); PG8_STAGE(PG8_SB(1, 0), b3, voffB);
;             PG8_BAR; PG8_WAIT_L(0); PG8_MMA(0, 1, At, B1); PG8_BAR;
;             PG8_LDA(At, 1, 1); PG8_STAGE(PG8_SA(1, 0), a3, voffA);
;             PG8_BAR; PG8_WAIT_L(0); PG8_MMA(1, 0, At, B0); PG8_BAR; PG8_SCHED;
;             PG8_STAGE(PG8_SB(1, 1), b3 + hstep, voffB);
;             PG8_WAIT_V(6); PG8_BAR; PG8_MMA(1, 1, At, B1); PG8_BAR;
	s_add_u32 s60, s14, 0x40000
	s_addc_u32 s61, s15, 0
	s_add_i32 s62, s62, s21
	v_lshl_add_u64 v[60:61], s[60:61], 0, v[190:191]
	s_mov_b32 m0, s62
	s_nop 0
	global_load_lds_dwordx4 v[60:61], off
	v_lshl_add_u64 v[60:61], s[60:61], 0, v[168:169]
	s_add_i32 m0, s62, 0x2000
	s_nop 0
	global_load_lds_dwordx4 v[60:61], off
	s_waitcnt vmcnt(6)
	s_barrier
	s_setprio 1
	v_mfma_f32_16x16x32_bf16 v[56:59], v[194:197], v[120:123], v[56:59]
	v_mfma_f32_16x16x32_bf16 v[48:51], v[204:207], v[120:123], v[48:51]
	v_mfma_f32_16x16x32_bf16 v[40:43], v[194:197], v[136:139], v[40:43]
	v_mfma_f32_16x16x32_bf16 v[32:35], v[204:207], v[136:139], v[32:35]
	v_mfma_f32_16x16x32_bf16 v[24:27], v[194:197], v[160:163], v[24:27]
	v_mfma_f32_16x16x32_bf16 v[16:19], v[204:207], v[160:163], v[16:19]
	v_mfma_f32_16x16x32_bf16 v[8:11], v[194:197], v[178:181], v[8:11]
	v_mfma_f32_16x16x32_bf16 v[0:3], v[204:207], v[178:181], v[0:3]
	v_mfma_f32_16x16x32_bf16 v[56:59], v[198:201], v[128:131], v[56:59]
	v_mfma_f32_16x16x32_bf16 v[48:51], v[208:211], v[128:131], v[48:51]
	v_mfma_f32_16x16x32_bf16 v[40:43], v[198:201], v[144:147], v[40:43]
	v_mfma_f32_16x16x32_bf16 v[32:35], v[208:211], v[144:147], v[32:35]
	v_mfma_f32_16x16x32_bf16 v[24:27], v[198:201], v[164:167], v[24:27]
	v_mfma_f32_16x16x32_bf16 v[16:19], v[208:211], v[164:167], v[16:19]
	v_mfma_f32_16x16x32_bf16 v[8:11], v[198:201], v[182:185], v[8:11]
	v_mfma_f32_16x16x32_bf16 v[0:3], v[208:211], v[182:185], v[0:3]
	s_setprio 0
	s_add_i32 s60, 0, 0x18000
	v_add_u32_e32 v76, s60, v217
	s_barrier
	ds_read_b128 v[60:63], v76
	ds_read_b128 v[64:67], v76 offset:1024
	ds_read_b128 v[72:75], v76 offset:2048
	ds_read_b128 v[76:79], v76 offset:3072
	s_add_u32 s16, s16, 0x40000
	s_addc_u32 s17, s17, 0
	s_mov_b32 m0, s30
	v_lshl_add_u64 v[136:137], s[16:17], 0, v[172:173]
	ds_read_b128 v[120:123], v223 offset:32768
	ds_read_b128 v[128:131], v223 offset:33792
	ds_read_b128 v[160:163], v223 offset:34816
	ds_read_b128 v[164:167], v223 offset:35840
	ds_read_b128 v[178:181], v223 offset:36864
	ds_read_b128 v[182:185], v223 offset:37888
	ds_read_b128 v[194:197], v223 offset:38912
	ds_read_b128 v[198:201], v223 offset:39936
	global_load_lds_dwordx4 v[136:137], off
	v_lshl_add_u64 v[136:137], s[16:17], 0, v[170:171]
	s_mov_b32 m0, s31
	s_nop 0
	global_load_lds_dwordx4 v[136:137], off
	s_waitcnt lgkmcnt(8)
	s_barrier
	s_waitcnt lgkmcnt(0)
	s_setprio 1
	s_waitcnt lgkmcnt(0)
	v_mfma_f32_16x16x32_bf16 v[136:139], v[60:63], v[120:123], v[156:159]
	v_mfma_f32_16x16x32_bf16 v[156:159], v[64:67], v[128:131], v[136:139]
	v_mfma_f32_16x16x32_bf16 v[136:139], v[72:75], v[120:123], v[148:151]
	v_mfma_f32_16x16x32_bf16 v[148:151], v[76:79], v[128:131], v[136:139]
	v_mfma_f32_16x16x32_bf16 v[136:139], v[60:63], v[160:163], v[140:143]
	v_mfma_f32_16x16x32_bf16 v[132:135], v[72:75], v[160:163], v[132:135]
	v_mfma_f32_16x16x32_bf16 v[124:127], v[60:63], v[178:181], v[124:127]
	v_mfma_f32_16x16x32_bf16 v[116:119], v[72:75], v[178:181], v[116:119]
	v_mfma_f32_16x16x32_bf16 v[108:111], v[60:63], v[194:197], v[108:111]
	v_mfma_f32_16x16x32_bf16 v[100:103], v[72:75], v[194:197], v[100:103]
	v_mfma_f32_16x16x32_bf16 v[140:143], v[64:67], v[164:167], v[136:139]
	v_mfma_f32_16x16x32_bf16 v[132:135], v[76:79], v[164:167], v[132:135]
	v_mfma_f32_16x16x32_bf16 v[124:127], v[64:67], v[182:185], v[124:127]
	v_mfma_f32_16x16x32_bf16 v[116:119], v[76:79], v[182:185], v[116:119]
	v_mfma_f32_16x16x32_bf16 v[108:111], v[64:67], v[198:201], v[108:111]
	v_mfma_f32_16x16x32_bf16 v[100:103], v[76:79], v[198:201], v[100:103]
	s_setprio 0
	s_barrier
	s_add_i32 s16, 0, 0x1c000
	v_add_u32_e32 v136, s16, v217
	s_add_i32 s17, s60, s21
	ds_read_b128 v[204:207], v136
	ds_read_b128 v[208:211], v136 offset:1024
	ds_read_b128 v[212:215], v136 offset:2048
	ds_read_b128 v[218:221], v136 offset:3072
	v_lshl_add_u64 v[136:137], v[188:189], 0, s[28:29]
	s_mov_b32 m0, s17
	s_nop 0
	global_load_lds_dwordx4 v[136:137], off
	v_lshl_add_u64 v[136:137], v[224:225], 0, s[28:29]
	s_add_i32 m0, s17, 0x2000
	s_nop 0
	global_load_lds_dwordx4 v[136:137], off
	s_barrier
	s_waitcnt lgkmcnt(0)
	s_setprio 1
	s_waitcnt lgkmcnt(0)
	v_mfma_f32_16x16x32_bf16 v[80:83], v[212:215], v[120:123], v[80:83]
	v_mfma_f32_16x16x32_bf16 v[136:139], v[204:207], v[120:123], v[152:155]
	v_mfma_f32_16x16x32_bf16 v[144:147], v[218:221], v[128:131], v[80:83]
	v_mfma_f32_16x16x32_bf16 v[80:83], v[204:207], v[160:163], v[84:87]
	v_mfma_f32_16x16x32_bf16 v[152:155], v[208:211], v[128:131], v[136:139]
	v_mfma_f32_16x16x32_bf16 v[136:139], v[208:211], v[164:167], v[80:83]
	v_mfma_f32_16x16x32_bf16 v[80:83], v[212:215], v[160:163], v[92:95]
	v_mfma_f32_16x16x32_bf16 v[128:131], v[218:221], v[164:167], v[80:83]
	v_mfma_f32_16x16x32_bf16 v[80:83], v[204:207], v[178:181], v[96:99]
	v_mfma_f32_16x16x32_bf16 v[120:123], v[208:211], v[182:185], v[80:83]
	v_mfma_f32_16x16x32_bf16 v[80:83], v[212:215], v[178:181], v[112:115]
	v_mfma_f32_16x16x32_bf16 v[112:115], v[218:221], v[182:185], v[80:83]
	v_mfma_f32_16x16x32_bf16 v[80:83], v[204:207], v[194:197], v[104:107]
	v_mfma_f32_16x16x32_bf16 v[104:107], v[208:211], v[198:201], v[80:83]
	v_mfma_f32_16x16x32_bf16 v[80:83], v[212:215], v[194:197], v[88:91]
	v_mfma_f32_16x16x32_bf16 v[88:91], v[218:221], v[198:201], v[80:83]
	s_setprio 0
	s_mov_b32 m0, s51
	v_lshl_add_u64 v[188:189], v[226:227], 0, s[28:29]
	s_barrier
	s_nop 2
	ds_read_b128 v[80:83], v223 offset:49152
	ds_read_b128 v[84:87], v223 offset:50176
	ds_read_b128 v[92:95], v223 offset:51200
	ds_read_b128 v[96:99], v223 offset:52224
	ds_read_b128 v[160:163], v223 offset:53248
	ds_read_b128 v[164:167], v223 offset:54272
	ds_read_b128 v[178:181], v223 offset:55296
	ds_read_b128 v[182:185], v223 offset:56320
	global_load_lds_dwordx4 v[188:189], off
	v_lshl_add_u64 v[188:189], v[240:241], 0, s[28:29]
	s_mov_b32 m0, s52
	s_nop 0
	global_load_lds_dwordx4 v[188:189], off
	s_barrier
; #define PG8_STAGE(bufoff, gbase, voff) do { _Pragma("unroll") for (int _i = 0; _i < 2; ++_i) \
;         __builtin_amdgcn_global_load_lds((const unsigned*)((const char*)(gbase) + (voff)[_i]), (LAS unsigned*)(lds + (bufoff) + ldsw + _i * 8192), 16, 0, 0); } while (0)
; #define PG8_LDA(dst, b, h) do { _Pragma("unroll") for (int m = 0; m < 4; ++m) _Pragma("unroll") for (int k = 0; k < 2; ++k) dst[m][k] = *(const LAS bf16x8*)(lds + PG8_SA(b, h) + aoff + m * 2048 + k * 1024); } while (0)
; #define PG8_LDB(dst, b, h) do { _Pragma("unroll") for (int n = 0; n < 2; ++n) _Pragma("unroll") for (int k = 0; k < 2; ++k) dst[n][k] = *(const LAS bf16x8*)(lds + PG8_SB(b, h) + boff + n * 2048 + k * 1024); } while (0)
; template <class Epi>
; __device__ __forceinline__ void gemm_phase(LAS unsigned char* lds, const Gemm g, const StaticOrder& S, const Epi& E) {
;     ...
;             PG8_BAR; PG8_WAIT_L(0); PG8_MMA(1, 0, At, B0); PG8_BAR; PG8_SCHED;
;             PG8_STAGE(PG8_SB(0, 1), b2 + hstep, voffB);
;             PG8_WAIT_V(6); PG8_BAR; PG8_MMA(1, 1, At, B1); PG8_BAR;
;             PG8_LDB(B0, 1, 0); PG8_SCHED; PG8_LDA(At, 1, 0); PG8_STAGE(PG8_SA(0, 1), a2 + hstep, voffA);
;             PG8_WAIT_L(8); PG8_BAR; PG8_WAIT_L(0); PG8_MMA(0, 0, At, B0); PG8_BAR; PG8_SCHED;
;             PG8_LDB(B1, 1, 1); PG8_STAGE(PG8_SB(1, 0), b3, voffB);
;             PG8_BAR; PG8_WAIT_L(0); PG8_MMA(0, 1, At, B1); PG8_BAR;
;             PG8_LDA(At, 1, 1); PG8_STAGE(PG8_SA(1, 0), a3, voffA);
;             PG8_BAR; PG8_WAIT_L(0); PG8_MMA(1, 0, At, B0); PG8_BAR; PG8_SCHED;
;             PG8_STAGE(PG8_SB(1, 1), b3 + hstep, voffB);
;             PG8_WAIT_V(6); PG8_BAR; PG8_MMA(1, 1, At, B1); PG8_BAR;
;         }
;     __device__ __forceinline__ void operator()(const f32x4 (&acc)[2][2][4][2], const Unit& u, int wr, int wc, int fr_, int fq_) const {
;     ...
;         const int lc = wc * 32 + fq * 8;
;         f32x4 c1v[2][2], c2v[2][2];
; #pragma unroll
;         for (int bj = 0; bj < 2; ++bj)
; #pragma unroll
;             for (int n = 0; n < 2; ++n) { c1v[bj][n] = *(const f32x4*)(c1 + u.pn * 256 + bj * 128 + lc + 4 * n); c2v[bj][n] = *(const f32x4*)(c2 + u.pn * 256 + bj * 128 + lc + 4 * n); }
;         float mus[8], rss[8];
; #pragma unroll
;         for (int q = 0; q < 8; ++q) row_stats(st1, u.pm * 256 + (q >> 2) * 128 + (q & 3) * 16 + wr * 64 + fr, fq, mus[q], rss[q]);
	s_waitcnt lgkmcnt(0)
	s_setprio 1
	s_waitcnt lgkmcnt(0)
	v_mfma_f32_16x16x32_bf16 v[68:71], v[60:63], v[80:83], v[68:71]
	v_mfma_f32_16x16x32_bf16 v[52:55], v[72:75], v[80:83], v[52:55]
	v_mfma_f32_16x16x32_bf16 v[44:47], v[60:63], v[92:95], v[44:47]
	v_mfma_f32_16x16x32_bf16 v[36:39], v[72:75], v[92:95], v[36:39]
	v_mfma_f32_16x16x32_bf16 v[28:31], v[60:63], v[160:163], v[28:31]
	v_mfma_f32_16x16x32_bf16 v[20:23], v[72:75], v[160:163], v[20:23]
	v_mfma_f32_16x16x32_bf16 v[12:15], v[60:63], v[178:181], v[12:15]
	v_mfma_f32_16x16x32_bf16 v[4:7], v[72:75], v[178:181], v[4:7]
	v_mfma_f32_16x16x32_bf16 v[68:71], v[64:67], v[84:87], v[68:71]
	v_mfma_f32_16x16x32_bf16 v[52:55], v[76:79], v[84:87], v[52:55]
	v_mfma_f32_16x16x32_bf16 v[44:47], v[64:67], v[96:99], v[44:47]
	v_mfma_f32_16x16x32_bf16 v[36:39], v[76:79], v[96:99], v[36:39]
	v_mfma_f32_16x16x32_bf16 v[28:31], v[64:67], v[164:167], v[28:31]
	v_mfma_f32_16x16x32_bf16 v[20:23], v[76:79], v[164:167], v[20:23]
	v_mfma_f32_16x16x32_bf16 v[12:15], v[64:67], v[182:185], v[12:15]
	v_mfma_f32_16x16x32_bf16 v[4:7], v[76:79], v[182:185], v[4:7]
	s_setprio 0
	s_barrier
	s_add_u32 s14, s14, 0x40080
	s_addc_u32 s15, s15, 0
	s_add_i32 s16, s16, s21
	v_lshl_add_u64 v[60:61], s[14:15], 0, v[190:191]
	s_mov_b32 m0, s16
	s_nop 0
	global_load_lds_dwordx4 v[60:61], off
	v_lshl_add_u64 v[60:61], s[14:15], 0, v[168:169]
	s_add_i32 m0, s16, 0x2000
	s_nop 0
	global_load_lds_dwordx4 v[60:61], off
	s_waitcnt vmcnt(6)
	s_barrier
	s_setprio 1
	v_mfma_f32_16x16x32_bf16 v[56:59], v[204:207], v[80:83], v[56:59]
	v_mfma_f32_16x16x32_bf16 v[48:51], v[212:215], v[80:83], v[48:51]
	v_mfma_f32_16x16x32_bf16 v[40:43], v[204:207], v[92:95], v[40:43]
	v_mfma_f32_16x16x32_bf16 v[32:35], v[212:215], v[92:95], v[32:35]
	v_mfma_f32_16x16x32_bf16 v[24:27], v[204:207], v[160:163], v[24:27]
	v_mfma_f32_16x16x32_bf16 v[16:19], v[212:215], v[160:163], v[16:19]
	v_mfma_f32_16x16x32_bf16 v[8:11], v[204:207], v[178:181], v[8:11]
	v_mfma_f32_16x16x32_bf16 v[0:3], v[212:215], v[178:181], v[0:3]
	v_mfma_f32_16x16x32_bf16 v[56:59], v[208:211], v[84:87], v[56:59]
	v_mfma_f32_16x16x32_bf16 v[48:51], v[218:221], v[84:87], v[48:51]
	v_mfma_f32_16x16x32_bf16 v[40:43], v[208:211], v[96:99], v[40:43]
	v_mfma_f32_16x16x32_bf16 v[32:35], v[218:221], v[96:99], v[32:35]
	v_mfma_f32_16x16x32_bf16 v[24:27], v[208:211], v[164:167], v[24:27]
	v_mfma_f32_16x16x32_bf16 v[16:19], v[218:221], v[164:167], v[16:19]
	v_mfma_f32_16x16x32_bf16 v[8:11], v[208:211], v[182:185], v[8:11]
	v_mfma_f32_16x16x32_bf16 v[0:3], v[218:221], v[182:185], v[0:3]
	s_setprio 0
	s_add_i32 s59, s59, 2
	s_add_u32 s10, s10, 0x100
	s_addc_u32 s11, s11, 0
	s_add_u32 s57, s57, 0x100
	s_addc_u32 s58, s58, 0
	s_cmp_gt_u32 s59, 13
	s_barrier
	s_cbranch_scc0 .LBB0_878
	s_lshl_b32 s10, s54, 8
	s_ashr_i32 s11, s10, 31
	s_lshl_b64 s[10:11], s[10:11], 2
	s_add_u32 s14, s2, s10
	s_addc_u32 s15, s46, s11
	v_xor_b32_e32 v162, 16, v231
	s_add_u32 s10, s47, s10
	v_cmp_lt_i32_e32 vcc, v162, v232
	v_mov_b32_e32 v161, v187
	v_mov_b32_e32 v60, v203
	s_addc_u32 s11, s48, s11
	s_lshl_b32 s1, s5, 8
	v_cndmask_b32_e32 v162, v231, v162, vcc
	s_add_i32 s1, s1, s49
	v_lshlrev_b32_e32 v160, 3, v60
	v_lshlrev_b32_e32 v239, 2, v162
	v_xor_b32_e32 v162, 32, v231
	v_add_u32_e32 v188, s50, v160
	v_add_u32_e32 v210, s1, v161
	v_readlane_b32 s4, v253, 21
	v_cmp_lt_i32_e32 vcc, v162, v232
	v_ashrrev_i32_e32 v189, 31, v188
	v_ashrrev_i32_e32 v161, 31, v160
	v_readlane_b32 s5, v253, 22
	v_cndmask_b32_e32 v162, v231, v162, vcc
	v_ashrrev_i32_e32 v211, 31, v210
	v_lshlrev_b64 v[60:61], 2, v[188:189]
	v_lshl_add_u64 v[160:161], v[160:161], 2, s[4:5]
	v_lshlrev_b32_e32 v225, 2, v162
	v_lshlrev_b64 v[162:163], 7, v[210:211]
	v_lshl_add_u64 v[64:65], s[14:15], 0, v[60:61]
	v_lshl_add_u64 v[84:85], s[10:11], 0, v[60:61]
	v_lshl_add_u64 v[166:167], v[160:161], 0, v[162:163]
	v_and_b32_e32 v194, 48, v231
	v_mov_b32_e32 v195, 0
	v_lshlrev_b32_e32 v194, 7, v194
	v_lshl_add_u64 v[196:197], v[166:167], 0, v[194:195]
	global_load_dword v198, v[196:197], off
	v_add_u32_e32 v194, 0x4000, v194
	v_lshl_add_u64 v[196:197], v[166:167], 0, v[194:195]
	global_load_dword v199, v[196:197], off
	global_load_dwordx4 v[72:75], v[64:65], off offset:16
	global_load_dwordx4 v[92:95], v[64:65], off
	global_load_dwordx4 v[76:79], v[84:85], off offset:16
	global_load_dwordx4 v[96:99], v[84:85], off
	global_load_dwordx4 v[60:63], v[64:65], off offset:528
	global_load_dwordx4 v[80:83], v[64:65], off offset:512
	s_nop 0
	global_load_dwordx4 v[64:67], v[84:85], off offset:528
	s_nop 0
	global_load_dwordx4 v[84:87], v[84:85], off offset:512
	s_nop 0
	global_load_dwordx4 v[162:165], v[166:167], off offset:16
	global_load_dwordx4 v[178:181], v[166:167], off
	v_add_u32_e32 v204, 16, v210
	v_ashrrev_i32_e32 v205, 31, v204
	v_add_u32_e32 v208, 0x90, v210
	v_ashrrev_i32_e32 v209, 31, v208
	v_add_u32_e32 v212, 0xa0, v210
	v_ashrrev_i32_e32 v213, 31, v212
	s_lshl_b32 s10, s54, 7
	s_ashr_i32 s11, s10, 31
	s_movk_i32 s1, 0x1600
	s_lshl_b64 s[10:11], s[10:11], 1
	s_mov_b32 s54, s0
	s_mov_b32 s5, s38
	s_waitcnt vmcnt(0)
	v_mov_b32_e32 v167, v162
	v_mov_b32_e32 v166, v178
	v_mov_b32_e32 v182, v180
	v_mov_b32_e32 v183, v164
	v_pk_add_f32 v[166:167], v[166:167], v[182:183]
	v_add_f32_e32 v162, v179, v181
	v_add_f32_e32 v164, v163, v165
	v_mov_b32_e32 v163, v166
	v_mov_b32_e32 v165, v167
	v_pk_add_f32 v[162:163], v[162:163], v[164:165]
	ds_bpermute_b32 v165, v239, v163
	ds_bpermute_b32 v164, v239, v162
	s_waitcnt lgkmcnt(0)
	v_pk_add_f32 v[162:163], v[162:163], v[164:165]
	ds_bpermute_b32 v165, v225, v163
	ds_bpermute_b32 v164, v225, v162
	s_waitcnt lgkmcnt(0)
; __device__ __forceinline__ void row_stats(const float* st, int row, int fq, float& mu, float& rs) {
;     const f32x4 a = *(const f32x4*)(st + (size_t)row * 32 + fq * 8), b = *(const f32x4*)(st + (size_t)row * 32 + fq * 8 + 4);
;     float s = (a[0] + a[2]) + (b[0] + b[2]), q = (a[1] + a[3]) + (b[1] + b[3]);
;     s += __shfl_xor(s, 16); s += __shfl_xor(s, 32); q += __shfl_xor(q, 16); q += __shfl_xor(q, 32);
;     mu = s * (1.0f / 1024.0f); const float var = fmaxf(q * (1.0f / 1024.0f) - mu * mu, 0.f); rs = rsqrtf(var + LN_EPS);
;     __device__ __forceinline__ void operator()(const f32x4 (&acc)[2][2][4][2], const Unit& u, int wr, int wc, int fr_, int fq_) const {
;     ...
;         for (int q = 0; q < 8; ++q) row_stats(st1, u.pm * 256 + (q >> 2) * 128 + (q & 3) * 16 + wr * 64 + fr, fq, mus[q], rss[q]);
;         asm volatile("" ::: "memory");
; #pragma unroll
;         for (int ai = 0; ai < 2; ++ai)
; #pragma unroll
;             for (int m = 0; m < 4; ++m) {
;                 const int grow = u.pm * 256 + ai * 128 + m * 16 + wr * 64 + fr;
;                 const float mu = mus[ai * 4 + m], rs = rss[ai * 4 + m];
;                 f32x4 h[2];
; #pragma unroll
;                 for (int n = 0; n < 2; ++n) {
;                     const f32x4 g = (acc[ai][0][m][n] - mu * c1v[0][n]) * rs + c2v[0][n];
	v_pk_add_f32 v[162:163], v[162:163], v[164:165]
	s_nop 0
	v_pk_mul_f32 v[226:227], v[162:163], s[74:75] op_sel_hi:[1,0]
	s_nop 0
	v_fma_f32 v162, -v227, v227, v226
	v_max_f32_e32 v162, 0, v162
	v_add_f32_e32 v162, 0x3727c5ac, v162
	v_cmp_gt_f32_e32 vcc, s75, v162
	v_mul_f32_e32 v163, 0x4b800000, v162
	v_pk_fma_f32 v[156:157], v[92:93], v[226:227], v[156:157] op_sel:[0,1,0] neg_lo:[1,0,0] neg_hi:[1,0,0]
	v_cndmask_b32_e32 v162, v162, v163, vcc
	v_rsq_f32_e32 v162, v162
	v_pk_fma_f32 v[152:153], v[80:81], v[226:227], v[152:153] op_sel:[0,1,0] neg_lo:[1,0,0] neg_hi:[1,0,0]
	v_pk_fma_f32 v[154:155], v[82:83], v[226:227], v[154:155] op_sel:[0,1,0] neg_lo:[1,0,0] neg_hi:[1,0,0]
	v_pk_fma_f32 v[148:149], v[72:73], v[226:227], v[148:149] op_sel:[0,1,0] neg_lo:[1,0,0] neg_hi:[1,0,0]
	v_mul_f32_e32 v163, 0x45800000, v162
	v_cndmask_b32_e32 v228, v162, v163, vcc
	v_lshlrev_b64 v[162:163], 7, v[204:205]
	v_lshl_add_u64 v[166:167], v[160:161], 0, v[162:163]
	global_load_dwordx4 v[162:165], v[166:167], off offset:16
	global_load_dwordx4 v[178:181], v[166:167], off
	v_pk_fma_f32 v[156:157], v[156:157], v[228:229], v[96:97] op_sel_hi:[1,0,1]
	v_pk_fma_f32 v[152:153], v[152:153], v[228:229], v[84:85] op_sel_hi:[1,0,1]
	v_pk_fma_f32 v[154:155], v[154:155], v[228:229], v[86:87] op_sel_hi:[1,0,1]
	v_pk_fma_f32 v[148:149], v[148:149], v[228:229], v[76:77] op_sel_hi:[1,0,1]
	v_pk_fma_f32 v[144:145], v[60:61], v[226:227], v[144:145] op_sel:[0,1,0] neg_lo:[1,0,0] neg_hi:[1,0,0]
	v_pk_fma_f32 v[146:147], v[62:63], v[226:227], v[146:147] op_sel:[0,1,0] neg_lo:[1,0,0] neg_hi:[1,0,0]
	v_pk_fma_f32 v[144:145], v[144:145], v[228:229], v[64:65] op_sel_hi:[1,0,1]
	v_pk_fma_f32 v[146:147], v[146:147], v[228:229], v[66:67] op_sel_hi:[1,0,1]
	s_waitcnt vmcnt(1)
	v_mov_b32_e32 v167, v162
	s_waitcnt vmcnt(0)
	v_mov_b32_e32 v166, v178
	v_mov_b32_e32 v182, v180
	v_mov_b32_e32 v183, v164
	v_pk_add_f32 v[166:167], v[166:167], v[182:183]
	v_add_f32_e32 v162, v179, v181
	v_add_f32_e32 v164, v163, v165
	v_mov_b32_e32 v163, v166
	v_mov_b32_e32 v165, v167
	v_pk_add_f32 v[162:163], v[162:163], v[164:165]
	ds_bpermute_b32 v165, v239, v163
	ds_bpermute_b32 v164, v239, v162
	v_add_u32_e32 v182, 32, v210
	v_ashrrev_i32_e32 v183, 31, v182
	s_waitcnt lgkmcnt(0)
	v_pk_add_f32 v[162:163], v[162:163], v[164:165]
	ds_bpermute_b32 v165, v225, v163
	ds_bpermute_b32 v164, v225, v162
	s_waitcnt lgkmcnt(0)
	v_pk_add_f32 v[162:163], v[162:163], v[164:165]
	s_nop 0
	v_pk_mul_f32 v[214:215], v[162:163], s[74:75] op_sel_hi:[1,0]
	s_nop 0
	v_fma_f32 v162, -v215, v215, v214
	v_max_f32_e32 v162, 0, v162
	v_add_f32_e32 v162, 0x3727c5ac, v162
	v_cmp_gt_f32_e32 vcc, s75, v162
	v_mul_f32_e32 v163, 0x4b800000, v162
	v_pk_fma_f32 v[140:141], v[92:93], v[214:215], v[140:141] op_sel:[0,1,0] neg_lo:[1,0,0] neg_hi:[1,0,0]
	v_cndmask_b32_e32 v162, v162, v163, vcc
	v_rsq_f32_e32 v162, v162
	v_pk_fma_f32 v[136:137], v[80:81], v[214:215], v[136:137] op_sel:[0,1,0] neg_lo:[1,0,0] neg_hi:[1,0,0]
	v_pk_fma_f32 v[138:139], v[82:83], v[214:215], v[138:139] op_sel:[0,1,0] neg_lo:[1,0,0] neg_hi:[1,0,0]
	v_pk_fma_f32 v[132:133], v[72:73], v[214:215], v[132:133] op_sel:[0,1,0] neg_lo:[1,0,0] neg_hi:[1,0,0]
	v_mul_f32_e32 v163, 0x45800000, v162
	v_cndmask_b32_e32 v216, v162, v163, vcc
	v_lshlrev_b64 v[162:163], 7, v[182:183]
	v_lshl_add_u64 v[166:167], v[160:161], 0, v[162:163]
	global_load_dwordx4 v[162:165], v[166:167], off offset:16
	global_load_dwordx4 v[178:181], v[166:167], off
	v_pk_fma_f32 v[140:141], v[140:141], v[216:217], v[96:97] op_sel_hi:[1,0,1]
	v_pk_fma_f32 v[136:137], v[136:137], v[216:217], v[84:85] op_sel_hi:[1,0,1]
	v_pk_fma_f32 v[138:139], v[138:139], v[216:217], v[86:87] op_sel_hi:[1,0,1]
	v_pk_fma_f32 v[132:133], v[132:133], v[216:217], v[76:77] op_sel_hi:[1,0,1]
	v_pk_fma_f32 v[128:129], v[60:61], v[214:215], v[128:129] op_sel:[0,1,0] neg_lo:[1,0,0] neg_hi:[1,0,0]
	v_pk_fma_f32 v[130:131], v[62:63], v[214:215], v[130:131] op_sel:[0,1,0] neg_lo:[1,0,0] neg_hi:[1,0,0]
	v_pk_fma_f32 v[128:129], v[128:129], v[216:217], v[64:65] op_sel_hi:[1,0,1]
	v_pk_fma_f32 v[130:131], v[130:131], v[216:217], v[66:67] op_sel_hi:[1,0,1]
	s_waitcnt vmcnt(1)
	v_mov_b32_e32 v167, v162
	s_waitcnt vmcnt(0)
	v_mov_b32_e32 v166, v178
	v_mov_b32_e32 v184, v180
	v_mov_b32_e32 v185, v164
	v_pk_add_f32 v[166:167], v[166:167], v[184:185]
	v_add_f32_e32 v162, v179, v181
	v_add_f32_e32 v164, v163, v165
	v_mov_b32_e32 v163, v166
	v_mov_b32_e32 v165, v167
	v_pk_add_f32 v[162:163], v[162:163], v[164:165]
	ds_bpermute_b32 v165, v239, v163
	ds_bpermute_b32 v164, v239, v162
	v_add_u32_e32 v184, 48, v210
	v_ashrrev_i32_e32 v185, 31, v184
	s_waitcnt lgkmcnt(0)
	v_pk_add_f32 v[162:163], v[162:163], v[164:165]
	ds_bpermute_b32 v165, v225, v163
	ds_bpermute_b32 v164, v225, v162
	s_waitcnt lgkmcnt(0)
; __device__ __forceinline__ void row_stats(const float* st, int row, int fq, float& mu, float& rs) {
;     const f32x4 a = *(const f32x4*)(st + (size_t)row * 32 + fq * 8), b = *(const f32x4*)(st + (size_t)row * 32 + fq * 8 + 4);
;     float s = (a[0] + a[2]) + (b[0] + b[2]), q = (a[1] + a[3]) + (b[1] + b[3]);
;     s += __shfl_xor(s, 16); s += __shfl_xor(s, 32); q += __shfl_xor(q, 16); q += __shfl_xor(q, 32);
;     mu = s * (1.0f / 1024.0f); const float var = fmaxf(q * (1.0f / 1024.0f) - mu * mu, 0.f); rs = rsqrtf(var + LN_EPS);
;     __device__ __forceinline__ void operator()(const f32x4 (&acc)[2][2][4][2], const Unit& u, int wr, int wc, int fr_, int fq_) const {
;     ...
;         for (int q = 0; q < 8; ++q) row_stats(st1, u.pm * 256 + (q >> 2) * 128 + (q & 3) * 16 + wr * 64 + fr, fq, mus[q], rss[q]);
;         asm volatile("" ::: "memory");
; #pragma unroll
;         for (int ai = 0; ai < 2; ++ai)
; #pragma unroll
;             for (int m = 0; m < 4; ++m) {
;                 const int grow = u.pm * 256 + ai * 128 + m * 16 + wr * 64 + fr;
;                 const float mu = mus[ai * 4 + m], rs = rss[ai * 4 + m];
;                 f32x4 h[2];
; #pragma unroll
;                 for (int n = 0; n < 2; ++n) {
;                     const f32x4 g = (acc[ai][0][m][n] - mu * c1v[0][n]) * rs + c2v[0][n];
	v_pk_add_f32 v[162:163], v[162:163], v[164:165]
	s_nop 0
	v_pk_mul_f32 v[200:201], v[162:163], s[74:75] op_sel_hi:[1,0]
	s_nop 0
	v_fma_f32 v162, -v201, v201, v200
	v_max_f32_e32 v162, 0, v162
	v_add_f32_e32 v162, 0x3727c5ac, v162
	v_cmp_gt_f32_e32 vcc, s75, v162
	v_mul_f32_e32 v163, 0x4b800000, v162
	v_pk_fma_f32 v[124:125], v[92:93], v[200:201], v[124:125] op_sel:[0,1,0] neg_lo:[1,0,0] neg_hi:[1,0,0]
	v_cndmask_b32_e32 v162, v162, v163, vcc
	v_rsq_f32_e32 v162, v162
	v_pk_fma_f32 v[120:121], v[80:81], v[200:201], v[120:121] op_sel:[0,1,0] neg_lo:[1,0,0] neg_hi:[1,0,0]
	v_pk_fma_f32 v[122:123], v[82:83], v[200:201], v[122:123] op_sel:[0,1,0] neg_lo:[1,0,0] neg_hi:[1,0,0]
	v_pk_fma_f32 v[116:117], v[72:73], v[200:201], v[116:117] op_sel:[0,1,0] neg_lo:[1,0,0] neg_hi:[1,0,0]
	v_mul_f32_e32 v163, 0x45800000, v162
	v_cndmask_b32_e32 v202, v162, v163, vcc
	v_lshlrev_b64 v[162:163], 7, v[184:185]
	v_lshl_add_u64 v[166:167], v[160:161], 0, v[162:163]
	global_load_dwordx4 v[162:165], v[166:167], off offset:16
	global_load_dwordx4 v[178:181], v[166:167], off
	v_pk_fma_f32 v[124:125], v[124:125], v[202:203], v[96:97] op_sel_hi:[1,0,1]
	v_pk_fma_f32 v[120:121], v[120:121], v[202:203], v[84:85] op_sel_hi:[1,0,1]
	v_pk_fma_f32 v[122:123], v[122:123], v[202:203], v[86:87] op_sel_hi:[1,0,1]
	v_pk_fma_f32 v[116:117], v[116:117], v[202:203], v[76:77] op_sel_hi:[1,0,1]
	v_pk_fma_f32 v[112:113], v[60:61], v[200:201], v[112:113] op_sel:[0,1,0] neg_lo:[1,0,0] neg_hi:[1,0,0]
	v_pk_fma_f32 v[114:115], v[62:63], v[200:201], v[114:115] op_sel:[0,1,0] neg_lo:[1,0,0] neg_hi:[1,0,0]
	v_pk_fma_f32 v[112:113], v[112:113], v[202:203], v[64:65] op_sel_hi:[1,0,1]
	v_pk_fma_f32 v[114:115], v[114:115], v[202:203], v[66:67] op_sel_hi:[1,0,1]
	s_waitcnt vmcnt(1)
	v_mov_b32_e32 v167, v162
	s_waitcnt vmcnt(0)
	v_mov_b32_e32 v166, v178
	v_mov_b32_e32 v194, v180
	v_mov_b32_e32 v195, v164
	v_pk_add_f32 v[166:167], v[166:167], v[194:195]
	v_add_f32_e32 v162, v179, v181
	v_add_f32_e32 v164, v163, v165
	v_mov_b32_e32 v163, v166
	v_mov_b32_e32 v165, v167
	v_pk_add_f32 v[162:163], v[162:163], v[164:165]
	ds_bpermute_b32 v165, v239, v163
	ds_bpermute_b32 v164, v239, v162
	v_add_u32_e32 v178, 0x80, v210
	v_ashrrev_i32_e32 v179, 31, v178
	s_waitcnt lgkmcnt(0)
	v_pk_add_f32 v[162:163], v[162:163], v[164:165]
	ds_bpermute_b32 v165, v225, v163
	ds_bpermute_b32 v164, v225, v162
	s_waitcnt lgkmcnt(0)
	v_pk_add_f32 v[162:163], v[162:163], v[164:165]
	s_nop 0
	v_pk_mul_f32 v[198:199], v[162:163], s[74:75] op_sel_hi:[1,0]
	s_nop 0
	v_fma_f32 v162, -v199, v199, v198
	v_max_f32_e32 v162, 0, v162
	v_add_f32_e32 v162, 0x3727c5ac, v162
	v_cmp_gt_f32_e32 vcc, s75, v162
	v_mul_f32_e32 v163, 0x4b800000, v162
	v_pk_fma_f32 v[108:109], v[92:93], v[198:199], v[108:109] op_sel:[0,1,0] neg_lo:[1,0,0] neg_hi:[1,0,0]
	v_cndmask_b32_e32 v162, v162, v163, vcc
	v_rsq_f32_e32 v162, v162
	v_pk_fma_f32 v[104:105], v[80:81], v[198:199], v[104:105] op_sel:[0,1,0] neg_lo:[1,0,0] neg_hi:[1,0,0]
	v_pk_fma_f32 v[106:107], v[82:83], v[198:199], v[106:107] op_sel:[0,1,0] neg_lo:[1,0,0] neg_hi:[1,0,0]
	v_pk_fma_f32 v[100:101], v[72:73], v[198:199], v[100:101] op_sel:[0,1,0] neg_lo:[1,0,0] neg_hi:[1,0,0]
	v_mul_f32_e32 v163, 0x45800000, v162
	v_cndmask_b32_e32 v192, v162, v163, vcc
	v_lshlrev_b64 v[162:163], 7, v[178:179]
	v_lshl_add_u64 v[166:167], v[160:161], 0, v[162:163]
	global_load_dwordx4 v[162:165], v[166:167], off offset:16
	global_load_dwordx4 v[194:197], v[166:167], off
	v_pk_fma_f32 v[108:109], v[108:109], v[192:193], v[96:97] op_sel_hi:[1,0,1]
	v_pk_fma_f32 v[104:105], v[104:105], v[192:193], v[84:85] op_sel_hi:[1,0,1]
	v_pk_fma_f32 v[106:107], v[106:107], v[192:193], v[86:87] op_sel_hi:[1,0,1]
	v_pk_fma_f32 v[100:101], v[100:101], v[192:193], v[76:77] op_sel_hi:[1,0,1]
	v_pk_fma_f32 v[88:89], v[60:61], v[198:199], v[88:89] op_sel:[0,1,0] neg_lo:[1,0,0] neg_hi:[1,0,0]
	v_pk_fma_f32 v[90:91], v[62:63], v[198:199], v[90:91] op_sel:[0,1,0] neg_lo:[1,0,0] neg_hi:[1,0,0]
	v_pk_fma_f32 v[88:89], v[88:89], v[192:193], v[64:65] op_sel_hi:[1,0,1]
	v_pk_fma_f32 v[90:91], v[90:91], v[192:193], v[66:67] op_sel_hi:[1,0,1]
	s_waitcnt vmcnt(1)
	v_mov_b32_e32 v167, v162
	s_waitcnt vmcnt(0)
	v_mov_b32_e32 v166, v194
	v_mov_b32_e32 v180, v196
	v_mov_b32_e32 v181, v164
	v_pk_add_f32 v[166:167], v[166:167], v[180:181]
	v_add_f32_e32 v162, v195, v197
	v_add_f32_e32 v164, v163, v165
	v_mov_b32_e32 v163, v166
	v_mov_b32_e32 v165, v167
	v_pk_add_f32 v[162:163], v[162:163], v[164:165]
	ds_bpermute_b32 v165, v239, v163
	ds_bpermute_b32 v164, v239, v162
	s_waitcnt lgkmcnt(0)
	v_pk_add_f32 v[162:163], v[162:163], v[164:165]
	ds_bpermute_b32 v165, v225, v163
	ds_bpermute_b32 v164, v225, v162
	s_waitcnt lgkmcnt(0)
	v_pk_add_f32 v[162:163], v[162:163], v[164:165]
	s_nop 0
	v_pk_mul_f32 v[180:181], v[162:163], s[74:75] op_sel_hi:[1,0]
	s_nop 0
	v_fma_f32 v162, -v181, v181, v180
	v_max_f32_e32 v162, 0, v162
	v_add_f32_e32 v162, 0x3727c5ac, v162
	v_cmp_gt_f32_e32 vcc, s75, v162
	v_mul_f32_e32 v163, 0x4b800000, v162
	v_pk_fma_f32 v[68:69], v[92:93], v[180:181], v[68:69] op_sel:[0,1,0] neg_lo:[1,0,0] neg_hi:[1,0,0]
	v_cndmask_b32_e32 v162, v162, v163, vcc
	v_rsq_f32_e32 v162, v162
	v_pk_fma_f32 v[56:57], v[80:81], v[180:181], v[56:57] op_sel:[0,1,0] neg_lo:[1,0,0] neg_hi:[1,0,0]
	v_pk_fma_f32 v[58:59], v[82:83], v[180:181], v[58:59] op_sel:[0,1,0] neg_lo:[1,0,0] neg_hi:[1,0,0]
	v_pk_fma_f32 v[52:53], v[72:73], v[180:181], v[52:53] op_sel:[0,1,0] neg_lo:[1,0,0] neg_hi:[1,0,0]
	v_mul_f32_e32 v163, 0x45800000, v162
	v_cndmask_b32_e32 v186, v162, v163, vcc
	v_lshlrev_b64 v[162:163], 7, v[208:209]
	v_lshl_add_u64 v[166:167], v[160:161], 0, v[162:163]
	global_load_dwordx4 v[162:165], v[166:167], off offset:16
	global_load_dwordx4 v[194:197], v[166:167], off
	v_pk_fma_f32 v[68:69], v[68:69], v[186:187], v[96:97] op_sel_hi:[1,0,1]
	v_pk_fma_f32 v[56:57], v[56:57], v[186:187], v[84:85] op_sel_hi:[1,0,1]
	v_pk_fma_f32 v[58:59], v[58:59], v[186:187], v[86:87] op_sel_hi:[1,0,1]
	v_pk_fma_f32 v[52:53], v[52:53], v[186:187], v[76:77] op_sel_hi:[1,0,1]
	v_pk_fma_f32 v[48:49], v[60:61], v[180:181], v[48:49] op_sel:[0,1,0] neg_lo:[1,0,0] neg_hi:[1,0,0]
	v_pk_fma_f32 v[50:51], v[62:63], v[180:181], v[50:51] op_sel:[0,1,0] neg_lo:[1,0,0] neg_hi:[1,0,0]
	v_pk_fma_f32 v[48:49], v[48:49], v[186:187], v[64:65] op_sel_hi:[1,0,1]
	v_pk_fma_f32 v[50:51], v[50:51], v[186:187], v[66:67] op_sel_hi:[1,0,1]
	s_waitcnt vmcnt(1)
; __device__ __forceinline__ void row_stats(const float* st, int row, int fq, float& mu, float& rs) {
;     const f32x4 a = *(const f32x4*)(st + (size_t)row * 32 + fq * 8), b = *(const f32x4*)(st + (size_t)row * 32 + fq * 8 + 4);
;     float s = (a[0] + a[2]) + (b[0] + b[2]), q = (a[1] + a[3]) + (b[1] + b[3]);
;     s += __shfl_xor(s, 16); s += __shfl_xor(s, 32); q += __shfl_xor(q, 16); q += __shfl_xor(q, 32);
;     mu = s * (1.0f / 1024.0f); const float var = fmaxf(q * (1.0f / 1024.0f) - mu * mu, 0.f); rs = rsqrtf(var + LN_EPS);
;     __device__ __forceinline__ void operator()(const f32x4 (&acc)[2][2][4][2], const Unit& u, int wr, int wc, int fr_, int fq_) const {
;     ...
;         for (int q = 0; q < 8; ++q) row_stats(st1, u.pm * 256 + (q >> 2) * 128 + (q & 3) * 16 + wr * 64 + fr, fq, mus[q], rss[q]);
;         asm volatile("" ::: "memory");
; #pragma unroll
;         for (int ai = 0; ai < 2; ++ai)
; #pragma unroll
;             for (int m = 0; m < 4; ++m) {
;                 const int grow = u.pm * 256 + ai * 128 + m * 16 + wr * 64 + fr;
;                 const float mu = mus[ai * 4 + m], rs = rss[ai * 4 + m];
;                 f32x4 h[2];
; #pragma unroll
;                 for (int n = 0; n < 2; ++n) {
;                     const f32x4 g = (acc[ai][0][m][n] - mu * c1v[0][n]) * rs + c2v[0][n];
	v_mov_b32_e32 v167, v162
	s_waitcnt vmcnt(0)
	v_mov_b32_e32 v166, v194
	v_mov_b32_e32 v206, v196
	v_mov_b32_e32 v207, v164
	v_pk_add_f32 v[166:167], v[166:167], v[206:207]
	v_add_f32_e32 v162, v195, v197
	v_add_f32_e32 v164, v163, v165
	v_mov_b32_e32 v163, v166
	v_mov_b32_e32 v165, v167
	v_pk_add_f32 v[162:163], v[162:163], v[164:165]
	ds_bpermute_b32 v165, v239, v163
	ds_bpermute_b32 v164, v239, v162
	s_waitcnt lgkmcnt(0)
	v_pk_add_f32 v[162:163], v[162:163], v[164:165]
	ds_bpermute_b32 v165, v225, v163
	ds_bpermute_b32 v164, v225, v162
	s_waitcnt lgkmcnt(0)
	v_pk_add_f32 v[162:163], v[162:163], v[164:165]
	s_nop 0
	v_pk_mul_f32 v[218:219], v[162:163], s[74:75] op_sel_hi:[1,0]
	s_nop 0
	v_fma_f32 v162, -v219, v219, v218
	v_max_f32_e32 v162, 0, v162
	v_add_f32_e32 v162, 0x3727c5ac, v162
	v_cmp_gt_f32_e32 vcc, s75, v162
	v_mul_f32_e32 v163, 0x4b800000, v162
	v_pk_fma_f32 v[44:45], v[92:93], v[218:219], v[44:45] op_sel:[0,1,0] neg_lo:[1,0,0] neg_hi:[1,0,0]
	v_cndmask_b32_e32 v162, v162, v163, vcc
	v_rsq_f32_e32 v162, v162
	v_pk_fma_f32 v[40:41], v[80:81], v[218:219], v[40:41] op_sel:[0,1,0] neg_lo:[1,0,0] neg_hi:[1,0,0]
	v_pk_fma_f32 v[42:43], v[82:83], v[218:219], v[42:43] op_sel:[0,1,0] neg_lo:[1,0,0] neg_hi:[1,0,0]
	v_pk_fma_f32 v[36:37], v[72:73], v[218:219], v[36:37] op_sel:[0,1,0] neg_lo:[1,0,0] neg_hi:[1,0,0]
	v_mul_f32_e32 v163, 0x45800000, v162
	v_cndmask_b32_e32 v222, v162, v163, vcc
	v_lshlrev_b64 v[162:163], 7, v[212:213]
	v_lshl_add_u64 v[166:167], v[160:161], 0, v[162:163]
	global_load_dwordx4 v[162:165], v[166:167], off offset:16
	global_load_dwordx4 v[194:197], v[166:167], off
	v_pk_fma_f32 v[44:45], v[44:45], v[222:223], v[96:97] op_sel_hi:[1,0,1]
	v_pk_fma_f32 v[40:41], v[40:41], v[222:223], v[84:85] op_sel_hi:[1,0,1]
	v_pk_fma_f32 v[42:43], v[42:43], v[222:223], v[86:87] op_sel_hi:[1,0,1]
	v_pk_fma_f32 v[36:37], v[36:37], v[222:223], v[76:77] op_sel_hi:[1,0,1]
	v_pk_fma_f32 v[32:33], v[60:61], v[218:219], v[32:33] op_sel:[0,1,0] neg_lo:[1,0,0] neg_hi:[1,0,0]
	v_pk_fma_f32 v[34:35], v[62:63], v[218:219], v[34:35] op_sel:[0,1,0] neg_lo:[1,0,0] neg_hi:[1,0,0]
	v_pk_fma_f32 v[32:33], v[32:33], v[222:223], v[64:65] op_sel_hi:[1,0,1]
	v_pk_fma_f32 v[34:35], v[34:35], v[222:223], v[66:67] op_sel_hi:[1,0,1]
	s_waitcnt vmcnt(1)
	v_mov_b32_e32 v167, v162
	s_waitcnt vmcnt(0)
	v_mov_b32_e32 v166, v194
	v_mov_b32_e32 v206, v196
	v_mov_b32_e32 v207, v164
	v_pk_add_f32 v[166:167], v[166:167], v[206:207]
	v_add_f32_e32 v162, v195, v197
	v_add_f32_e32 v164, v163, v165
	v_mov_b32_e32 v163, v166
	v_mov_b32_e32 v165, v167
	v_pk_add_f32 v[162:163], v[162:163], v[164:165]
	ds_bpermute_b32 v165, v239, v163
	ds_bpermute_b32 v164, v239, v162
	v_add_u32_e32 v206, 0xb0, v210
	v_ashrrev_i32_e32 v207, 31, v206
	s_waitcnt lgkmcnt(0)
	v_pk_add_f32 v[162:163], v[162:163], v[164:165]
	ds_bpermute_b32 v165, v225, v163
	ds_bpermute_b32 v164, v225, v162
	s_waitcnt lgkmcnt(0)
	v_pk_add_f32 v[162:163], v[162:163], v[164:165]
	s_nop 0
	v_pk_mul_f32 v[220:221], v[162:163], s[74:75] op_sel_hi:[1,0]
	s_nop 0
	v_fma_f32 v162, -v221, v221, v220
	v_max_f32_e32 v162, 0, v162
	v_add_f32_e32 v162, 0x3727c5ac, v162
	v_cmp_gt_f32_e32 vcc, s75, v162
	v_mul_f32_e32 v163, 0x4b800000, v162
	v_pk_fma_f32 v[28:29], v[92:93], v[220:221], v[28:29] op_sel:[0,1,0] neg_lo:[1,0,0] neg_hi:[1,0,0]
	v_cndmask_b32_e32 v162, v162, v163, vcc
	v_rsq_f32_e32 v162, v162
	v_pk_fma_f32 v[24:25], v[80:81], v[220:221], v[24:25] op_sel:[0,1,0] neg_lo:[1,0,0] neg_hi:[1,0,0]
	v_pk_fma_f32 v[26:27], v[82:83], v[220:221], v[26:27] op_sel:[0,1,0] neg_lo:[1,0,0] neg_hi:[1,0,0]
	v_pk_fma_f32 v[20:21], v[72:73], v[220:221], v[20:21] op_sel:[0,1,0] neg_lo:[1,0,0] neg_hi:[1,0,0]
	v_mul_f32_e32 v163, 0x45800000, v162
	v_cndmask_b32_e32 v224, v162, v163, vcc
	v_lshlrev_b64 v[162:163], 7, v[206:207]
	v_lshl_add_u64 v[164:165], v[160:161], 0, v[162:163]
	global_load_dwordx4 v[160:163], v[164:165], off offset:16
	s_nop 0
	global_load_dwordx4 v[164:167], v[164:165], off
	v_pk_fma_f32 v[28:29], v[28:29], v[224:225], v[96:97] op_sel_hi:[1,0,1]
	v_pk_fma_f32 v[24:25], v[24:25], v[224:225], v[84:85] op_sel_hi:[1,0,1]
	v_pk_fma_f32 v[26:27], v[26:27], v[224:225], v[86:87] op_sel_hi:[1,0,1]
	v_pk_fma_f32 v[20:21], v[20:21], v[224:225], v[76:77] op_sel_hi:[1,0,1]
	v_pk_fma_f32 v[16:17], v[60:61], v[220:221], v[16:17] op_sel:[0,1,0] neg_lo:[1,0,0] neg_hi:[1,0,0]
	v_pk_fma_f32 v[18:19], v[62:63], v[220:221], v[18:19] op_sel:[0,1,0] neg_lo:[1,0,0] neg_hi:[1,0,0]
	v_pk_fma_f32 v[16:17], v[16:17], v[224:225], v[64:65] op_sel_hi:[1,0,1]
	v_pk_fma_f32 v[18:19], v[18:19], v[224:225], v[66:67] op_sel_hi:[1,0,1]
	s_waitcnt vmcnt(1)
	v_mov_b32_e32 v195, v160
	s_waitcnt vmcnt(0)
	v_mov_b32_e32 v194, v164
	v_mov_b32_e32 v196, v166
	v_mov_b32_e32 v197, v162
	v_pk_add_f32 v[194:195], v[194:195], v[196:197]
	v_add_f32_e32 v160, v165, v167
	v_add_f32_e32 v162, v161, v163
	v_mov_b32_e32 v161, v194
	v_mov_b32_e32 v163, v195
	v_pk_add_f32 v[160:161], v[160:161], v[162:163]
	ds_bpermute_b32 v163, v239, v161
	ds_bpermute_b32 v162, v239, v160
	s_waitcnt lgkmcnt(0)
	v_pk_add_f32 v[160:161], v[160:161], v[162:163]
	ds_bpermute_b32 v163, v225, v161
	ds_bpermute_b32 v162, v225, v160
	s_waitcnt lgkmcnt(0)
; __device__ __forceinline__ float silu_f(float x) { return x * __builtin_amdgcn_rcpf(1.0f + __expf(-x)); }
; __device__ __forceinline__ u32x4 pack8(const f32x4 a, const f32x4 b) { u32x4 w; w.x = cvt_pk_bf16(a[0], a[1]); w.y = cvt_pk_bf16(a[2], a[3]); w.z = cvt_pk_bf16(b[0], b[1]); w.w = cvt_pk_bf16(b[2], b[3]); return w; }
;     __device__ __forceinline__ void operator()(const f32x4 (&acc)[2][2][4][2], const Unit& u, int wr, int wc, int fr_, int fq_) const {
;     ...
;         for (int ai = 0; ai < 2; ++ai)
; #pragma unroll
;             for (int m = 0; m < 4; ++m) {
;                 const int grow = u.pm * 256 + ai * 128 + m * 16 + wr * 64 + fr;
;                 const float mu = mus[ai * 4 + m], rs = rss[ai * 4 + m];
;                 f32x4 h[2];
; #pragma unroll
;                 for (int n = 0; n < 2; ++n) {
;                     const f32x4 g = (acc[ai][0][m][n] - mu * c1v[0][n]) * rs + c2v[0][n];
;                     const f32x4 up = (acc[ai][1][m][n] - mu * c1v[1][n]) * rs + c2v[1][n];
; #pragma unroll
;                     for (int j = 0; j < 4; ++j) h[n][j] = silu_f(g[j]) * up[j];
;                 }
;                 *(u32x4*)(H + (size_t)grow * KF2 + u.pn * 128 + lc) = pack8(h[0], h[1]);
;             }
	v_pk_add_f32 v[160:161], v[160:161], v[162:163]
	s_nop 0
	v_pk_mul_f32 v[160:161], v[160:161], s[74:75] op_sel_hi:[1,0]
	s_nop 0
	v_fma_f32 v162, -v161, v161, v160
	v_max_f32_e32 v162, 0, v162
	v_add_f32_e32 v162, 0x3727c5ac, v162
	v_cmp_gt_f32_e32 vcc, s75, v162
	v_mul_f32_e32 v163, 0x4b800000, v162
	v_pk_fma_f32 v[12:13], v[92:93], v[160:161], v[12:13] op_sel:[0,1,0] neg_lo:[1,0,0] neg_hi:[1,0,0]
	v_cndmask_b32_e32 v162, v162, v163, vcc
	v_rsq_f32_e32 v162, v162
	v_pk_fma_f32 v[8:9], v[80:81], v[160:161], v[8:9] op_sel:[0,1,0] neg_lo:[1,0,0] neg_hi:[1,0,0]
	v_pk_fma_f32 v[10:11], v[82:83], v[160:161], v[10:11] op_sel:[0,1,0] neg_lo:[1,0,0] neg_hi:[1,0,0]
	v_pk_fma_f32 v[4:5], v[72:73], v[160:161], v[4:5] op_sel:[0,1,0] neg_lo:[1,0,0] neg_hi:[1,0,0]
	v_mul_f32_e32 v163, 0x45800000, v162
	v_cndmask_b32_e32 v162, v162, v163, vcc
	v_mul_f32_e32 v163, 0xbfb8aa3b, v156
	v_exp_f32_e32 v163, v163
	v_pk_fma_f32 v[0:1], v[60:61], v[160:161], v[0:1] op_sel:[0,1,0] neg_lo:[1,0,0] neg_hi:[1,0,0]
	v_pk_fma_f32 v[2:3], v[62:63], v[160:161], v[2:3] op_sel:[0,1,0] neg_lo:[1,0,0] neg_hi:[1,0,0]
	s_and_b64 vcc, exec, s[40:41]
	v_add_f32_e32 v163, 1.0, v163
	v_rcp_f32_e32 v164, v163
	v_mul_f32_e32 v163, 0xbfb8aa3b, v157
	v_exp_f32_e32 v163, v163
	s_nop 0
	v_add_f32_e32 v163, 1.0, v163
	v_rcp_f32_e32 v165, v163
	v_pk_fma_f32 v[12:13], v[12:13], v[162:163], v[96:97] op_sel_hi:[1,0,1]
	v_pk_fma_f32 v[8:9], v[8:9], v[162:163], v[84:85] op_sel_hi:[1,0,1]
	v_pk_fma_f32 v[10:11], v[10:11], v[162:163], v[86:87] op_sel_hi:[1,0,1]
	v_pk_mul_f32 v[156:157], v[156:157], v[164:165]
	v_pk_fma_f32 v[4:5], v[4:5], v[162:163], v[76:77] op_sel_hi:[1,0,1]
	v_pk_mul_f32 v[152:153], v[152:153], v[156:157]
	v_pk_fma_f32 v[156:157], v[94:95], v[226:227], v[158:159] op_sel:[0,1,0] neg_lo:[1,0,0] neg_hi:[1,0,0]
	v_pk_fma_f32 v[0:1], v[0:1], v[162:163], v[64:65] op_sel_hi:[1,0,1]
	v_pk_fma_f32 v[156:157], v[156:157], v[228:229], v[98:99] op_sel_hi:[1,0,1]
	v_pk_fma_f32 v[2:3], v[2:3], v[162:163], v[66:67] op_sel_hi:[1,0,1]
	v_mul_f32_e32 v158, 0xbfb8aa3b, v156
	v_mul_f32_e32 v159, 0xbfb8aa3b, v157
	v_exp_f32_e32 v158, v158
	v_exp_f32_e32 v159, v159
	v_add_f32_e32 v158, 1.0, v158
	v_add_f32_e32 v159, 1.0, v159
	v_rcp_f32_e32 v158, v158
	v_rcp_f32_e32 v159, v159
	s_nop 0
	v_pk_mul_f32 v[156:157], v[156:157], v[158:159]
	s_nop 0
	v_pk_mul_f32 v[154:155], v[154:155], v[156:157]
	v_mul_f32_e32 v156, 0xbfb8aa3b, v148
	v_mul_f32_e32 v157, 0xbfb8aa3b, v149
	v_exp_f32_e32 v156, v156
	v_exp_f32_e32 v157, v157
	v_add_f32_e32 v156, 1.0, v156
	v_add_f32_e32 v157, 1.0, v157
	v_rcp_f32_e32 v156, v156
	v_rcp_f32_e32 v157, v157
	s_nop 0
	v_pk_mul_f32 v[148:149], v[148:149], v[156:157]
	s_nop 0
	v_pk_mul_f32 v[144:145], v[144:145], v[148:149]
	v_pk_fma_f32 v[148:149], v[74:75], v[226:227], v[150:151] op_sel:[0,1,0] neg_lo:[1,0,0] neg_hi:[1,0,0]
	s_nop 0
	v_pk_fma_f32 v[148:149], v[148:149], v[228:229], v[78:79] op_sel_hi:[1,0,1]
	s_nop 0
	v_mul_f32_e32 v150, 0xbfb8aa3b, v148
	v_mul_f32_e32 v151, 0xbfb8aa3b, v149
	v_exp_f32_e32 v150, v150
	v_exp_f32_e32 v151, v151
	v_add_f32_e32 v150, 1.0, v150
	v_add_f32_e32 v151, 1.0, v151
	v_rcp_f32_e32 v150, v150
	v_rcp_f32_e32 v151, v151
	s_nop 0
	v_pk_mul_f32 v[148:149], v[148:149], v[150:151]
	s_nop 0
	v_pk_mul_f32 v[146:147], v[146:147], v[148:149]
	v_cvt_pk_bf16_f32 v150, v144, v145
	v_mov_b64_e32 v[144:145], s[24:25]
	v_cvt_pk_bf16_f32 v151, v146, v147
	v_mad_i64_i32 v[146:147], s[14:15], v210, s1, v[144:145]
	v_cvt_pk_bf16_f32 v148, v152, v153
	v_lshl_add_u64 v[152:153], v[146:147], 0, s[10:11]
	v_lshlrev_b64 v[146:147], 1, v[188:189]
	v_cvt_pk_bf16_f32 v149, v154, v155
	v_lshl_add_u64 v[152:153], v[152:153], 0, v[146:147]
	global_store_dwordx4 v[152:153], v[148:151], off
	s_nop 1
	v_mul_f32_e32 v148, 0xbfb8aa3b, v140
	v_mul_f32_e32 v149, 0xbfb8aa3b, v141
	v_exp_f32_e32 v148, v148
	v_exp_f32_e32 v149, v149
	v_add_f32_e32 v148, 1.0, v148
	v_add_f32_e32 v149, 1.0, v149
	v_rcp_f32_e32 v148, v148
	v_rcp_f32_e32 v149, v149
	s_nop 0
	v_pk_mul_f32 v[140:141], v[140:141], v[148:149]
	s_nop 0
	v_pk_mul_f32 v[136:137], v[136:137], v[140:141]
	v_pk_fma_f32 v[140:141], v[94:95], v[214:215], v[142:143] op_sel:[0,1,0] neg_lo:[1,0,0] neg_hi:[1,0,0]
	s_nop 0
	v_pk_fma_f32 v[140:141], v[140:141], v[216:217], v[98:99] op_sel_hi:[1,0,1]
	s_nop 0
	v_mul_f32_e32 v142, 0xbfb8aa3b, v140
	v_mul_f32_e32 v143, 0xbfb8aa3b, v141
	v_exp_f32_e32 v142, v142
	v_exp_f32_e32 v143, v143
	v_add_f32_e32 v142, 1.0, v142
	v_add_f32_e32 v143, 1.0, v143
	v_rcp_f32_e32 v142, v142
	v_rcp_f32_e32 v143, v143
	s_nop 0
	v_pk_mul_f32 v[140:141], v[140:141], v[142:143]
	s_nop 0
	v_pk_mul_f32 v[138:139], v[138:139], v[140:141]
	v_mul_f32_e32 v140, 0xbfb8aa3b, v132
	v_mul_f32_e32 v141, 0xbfb8aa3b, v133
	v_exp_f32_e32 v140, v140
	v_exp_f32_e32 v141, v141
	v_add_f32_e32 v140, 1.0, v140
	v_add_f32_e32 v141, 1.0, v141
	v_rcp_f32_e32 v140, v140
	v_rcp_f32_e32 v141, v141
	s_nop 0
	v_pk_mul_f32 v[132:133], v[132:133], v[140:141]
	s_nop 0
	v_pk_mul_f32 v[132:133], v[128:129], v[132:133]
	v_pk_fma_f32 v[128:129], v[74:75], v[214:215], v[134:135] op_sel:[0,1,0] neg_lo:[1,0,0] neg_hi:[1,0,0]
	s_nop 0
	v_pk_fma_f32 v[128:129], v[128:129], v[216:217], v[78:79] op_sel_hi:[1,0,1]
	s_nop 0
	v_mul_f32_e32 v134, 0xbfb8aa3b, v128
	v_mul_f32_e32 v135, 0xbfb8aa3b, v129
	v_exp_f32_e32 v134, v134
	v_exp_f32_e32 v135, v135
	v_add_f32_e32 v134, 1.0, v134
	v_add_f32_e32 v135, 1.0, v135
	v_rcp_f32_e32 v134, v134
	v_rcp_f32_e32 v135, v135
	s_nop 0
	v_pk_mul_f32 v[128:129], v[128:129], v[134:135]
	s_nop 0
	v_pk_mul_f32 v[134:135], v[130:131], v[128:129]
	v_cvt_pk_bf16_f32 v130, v132, v133
	v_mad_i64_i32 v[132:133], s[14:15], v204, s1, v[144:145]
; __device__ __forceinline__ float silu_f(float x) { return x * __builtin_amdgcn_rcpf(1.0f + __expf(-x)); }
; __device__ __forceinline__ u32x4 pack8(const f32x4 a, const f32x4 b) { u32x4 w; w.x = cvt_pk_bf16(a[0], a[1]); w.y = cvt_pk_bf16(a[2], a[3]); w.z = cvt_pk_bf16(b[0], b[1]); w.w = cvt_pk_bf16(b[2], b[3]); return w; }
;     __device__ __forceinline__ void operator()(const f32x4 (&acc)[2][2][4][2], const Unit& u, int wr, int wc, int fr_, int fq_) const {
;     ...
;         for (int ai = 0; ai < 2; ++ai)
; #pragma unroll
;             for (int m = 0; m < 4; ++m) {
;                 const int grow = u.pm * 256 + ai * 128 + m * 16 + wr * 64 + fr;
;                 const float mu = mus[ai * 4 + m], rs = rss[ai * 4 + m];
;                 f32x4 h[2];
; #pragma unroll
;                 for (int n = 0; n < 2; ++n) {
;                     const f32x4 g = (acc[ai][0][m][n] - mu * c1v[0][n]) * rs + c2v[0][n];
;                     const f32x4 up = (acc[ai][1][m][n] - mu * c1v[1][n]) * rs + c2v[1][n];
; #pragma unroll
;                     for (int j = 0; j < 4; ++j) h[n][j] = silu_f(g[j]) * up[j];
;                 }
;                 *(u32x4*)(H + (size_t)grow * KF2 + u.pn * 128 + lc) = pack8(h[0], h[1]);
;             }
	v_lshl_add_u64 v[132:133], v[132:133], 0, s[10:11]
	v_cvt_pk_bf16_f32 v128, v136, v137
	v_cvt_pk_bf16_f32 v129, v138, v139
	v_cvt_pk_bf16_f32 v131, v134, v135
	v_lshl_add_u64 v[132:133], v[132:133], 0, v[146:147]
	global_store_dwordx4 v[132:133], v[128:131], off
	s_nop 1
	v_mul_f32_e32 v128, 0xbfb8aa3b, v124
	v_mul_f32_e32 v129, 0xbfb8aa3b, v125
	v_exp_f32_e32 v128, v128
	v_exp_f32_e32 v129, v129
	v_add_f32_e32 v128, 1.0, v128
	v_add_f32_e32 v129, 1.0, v129
	v_rcp_f32_e32 v128, v128
	v_rcp_f32_e32 v129, v129
	s_nop 0
	v_pk_mul_f32 v[124:125], v[124:125], v[128:129]
	s_nop 0
	v_pk_mul_f32 v[120:121], v[120:121], v[124:125]
	v_pk_fma_f32 v[124:125], v[94:95], v[200:201], v[126:127] op_sel:[0,1,0] neg_lo:[1,0,0] neg_hi:[1,0,0]
	s_nop 0
	v_pk_fma_f32 v[124:125], v[124:125], v[202:203], v[98:99] op_sel_hi:[1,0,1]
	s_nop 0
	v_mul_f32_e32 v126, 0xbfb8aa3b, v124
	v_mul_f32_e32 v127, 0xbfb8aa3b, v125
	v_exp_f32_e32 v126, v126
	v_exp_f32_e32 v127, v127
	v_add_f32_e32 v126, 1.0, v126
	v_add_f32_e32 v127, 1.0, v127
	v_rcp_f32_e32 v126, v126
	v_rcp_f32_e32 v127, v127
	s_nop 0
	v_pk_mul_f32 v[124:125], v[124:125], v[126:127]
	s_nop 0
	v_pk_mul_f32 v[122:123], v[122:123], v[124:125]
	v_mul_f32_e32 v124, 0xbfb8aa3b, v116
	v_mul_f32_e32 v125, 0xbfb8aa3b, v117
	v_exp_f32_e32 v124, v124
	v_exp_f32_e32 v125, v125
	v_add_f32_e32 v124, 1.0, v124
	v_add_f32_e32 v125, 1.0, v125
	v_rcp_f32_e32 v124, v124
	v_rcp_f32_e32 v125, v125
	s_nop 0
	v_pk_mul_f32 v[116:117], v[116:117], v[124:125]
	s_nop 0
	v_pk_mul_f32 v[116:117], v[112:113], v[116:117]
	v_pk_fma_f32 v[112:113], v[74:75], v[200:201], v[118:119] op_sel:[0,1,0] neg_lo:[1,0,0] neg_hi:[1,0,0]
	s_nop 0
	v_pk_fma_f32 v[112:113], v[112:113], v[202:203], v[78:79] op_sel_hi:[1,0,1]
	s_nop 0
	v_mul_f32_e32 v118, 0xbfb8aa3b, v112
	v_mul_f32_e32 v119, 0xbfb8aa3b, v113
	v_exp_f32_e32 v118, v118
	v_exp_f32_e32 v119, v119
	v_add_f32_e32 v118, 1.0, v118
	v_add_f32_e32 v119, 1.0, v119
	v_rcp_f32_e32 v118, v118
	v_rcp_f32_e32 v119, v119
	s_nop 0
	v_pk_mul_f32 v[112:113], v[112:113], v[118:119]
	s_nop 0
	v_pk_mul_f32 v[118:119], v[114:115], v[112:113]
	v_cvt_pk_bf16_f32 v114, v116, v117
	v_mad_i64_i32 v[116:117], s[14:15], v182, s1, v[144:145]
	v_lshl_add_u64 v[116:117], v[116:117], 0, s[10:11]
	v_cvt_pk_bf16_f32 v112, v120, v121
	v_cvt_pk_bf16_f32 v113, v122, v123
	v_cvt_pk_bf16_f32 v115, v118, v119
	v_lshl_add_u64 v[116:117], v[116:117], 0, v[146:147]
	global_store_dwordx4 v[116:117], v[112:115], off
	s_nop 1
	v_mul_f32_e32 v112, 0xbfb8aa3b, v108
	v_mul_f32_e32 v113, 0xbfb8aa3b, v109
	v_exp_f32_e32 v112, v112
	v_exp_f32_e32 v113, v113
	v_add_f32_e32 v112, 1.0, v112
	v_add_f32_e32 v113, 1.0, v113
	v_rcp_f32_e32 v112, v112
	v_rcp_f32_e32 v113, v113
	s_nop 0
	v_pk_mul_f32 v[108:109], v[108:109], v[112:113]
	s_nop 0
	v_pk_mul_f32 v[104:105], v[104:105], v[108:109]
	v_pk_fma_f32 v[108:109], v[94:95], v[198:199], v[110:111] op_sel:[0,1,0] neg_lo:[1,0,0] neg_hi:[1,0,0]
	s_nop 0
	v_pk_fma_f32 v[108:109], v[108:109], v[192:193], v[98:99] op_sel_hi:[1,0,1]
	s_nop 0
	v_mul_f32_e32 v110, 0xbfb8aa3b, v108
	v_mul_f32_e32 v111, 0xbfb8aa3b, v109
	v_exp_f32_e32 v110, v110
	v_exp_f32_e32 v111, v111
	v_add_f32_e32 v110, 1.0, v110
	v_add_f32_e32 v111, 1.0, v111
	v_rcp_f32_e32 v110, v110
	v_rcp_f32_e32 v111, v111
	s_nop 0
	v_pk_mul_f32 v[108:109], v[108:109], v[110:111]
	s_nop 0
	v_pk_mul_f32 v[106:107], v[106:107], v[108:109]
	v_mul_f32_e32 v108, 0xbfb8aa3b, v100
	v_mul_f32_e32 v109, 0xbfb8aa3b, v101
	v_exp_f32_e32 v108, v108
	v_exp_f32_e32 v109, v109
	v_add_f32_e32 v108, 1.0, v108
	v_add_f32_e32 v109, 1.0, v109
	v_rcp_f32_e32 v108, v108
	v_rcp_f32_e32 v109, v109
	s_nop 0
	v_pk_mul_f32 v[100:101], v[100:101], v[108:109]
	s_nop 0
	v_pk_mul_f32 v[100:101], v[88:89], v[100:101]
	v_pk_fma_f32 v[88:89], v[74:75], v[198:199], v[102:103] op_sel:[0,1,0] neg_lo:[1,0,0] neg_hi:[1,0,0]
	s_nop 0
	v_pk_fma_f32 v[88:89], v[88:89], v[192:193], v[78:79] op_sel_hi:[1,0,1]
	s_nop 0
	v_mul_f32_e32 v102, 0xbfb8aa3b, v88
	v_mul_f32_e32 v103, 0xbfb8aa3b, v89
	v_exp_f32_e32 v102, v102
	v_exp_f32_e32 v103, v103
	v_add_f32_e32 v102, 1.0, v102
	v_add_f32_e32 v103, 1.0, v103
	v_rcp_f32_e32 v102, v102
	v_rcp_f32_e32 v103, v103
	s_nop 0
	v_pk_mul_f32 v[88:89], v[88:89], v[102:103]
	s_nop 0
	v_pk_mul_f32 v[102:103], v[90:91], v[88:89]
	v_cvt_pk_bf16_f32 v90, v100, v101
	v_mad_i64_i32 v[100:101], s[14:15], v184, s1, v[144:145]
	v_lshl_add_u64 v[100:101], v[100:101], 0, s[10:11]
	v_cvt_pk_bf16_f32 v88, v104, v105
	v_cvt_pk_bf16_f32 v89, v106, v107
	v_cvt_pk_bf16_f32 v91, v102, v103
	v_lshl_add_u64 v[100:101], v[100:101], 0, v[146:147]
	global_store_dwordx4 v[100:101], v[88:91], off
	s_nop 1
	v_mul_f32_e32 v88, 0xbfb8aa3b, v68
	v_mul_f32_e32 v89, 0xbfb8aa3b, v69
	v_exp_f32_e32 v88, v88
	v_exp_f32_e32 v89, v89
	v_add_f32_e32 v88, 1.0, v88
	v_add_f32_e32 v89, 1.0, v89
	v_rcp_f32_e32 v88, v88
	v_rcp_f32_e32 v89, v89
	s_nop 0
	v_pk_mul_f32 v[68:69], v[68:69], v[88:89]
	s_nop 0
	v_pk_mul_f32 v[56:57], v[56:57], v[68:69]
	v_pk_fma_f32 v[68:69], v[94:95], v[180:181], v[70:71] op_sel:[0,1,0] neg_lo:[1,0,0] neg_hi:[1,0,0]
	s_nop 0
	v_pk_fma_f32 v[68:69], v[68:69], v[186:187], v[98:99] op_sel_hi:[1,0,1]
	s_nop 0
	v_mul_f32_e32 v70, 0xbfb8aa3b, v68
	v_mul_f32_e32 v71, 0xbfb8aa3b, v69
	v_exp_f32_e32 v70, v70
	v_exp_f32_e32 v71, v71
	v_add_f32_e32 v70, 1.0, v70
	v_add_f32_e32 v71, 1.0, v71
	v_rcp_f32_e32 v70, v70
	v_rcp_f32_e32 v71, v71
	s_nop 0
	v_pk_mul_f32 v[68:69], v[68:69], v[70:71]
	s_nop 0
	v_pk_mul_f32 v[58:59], v[58:59], v[68:69]
	v_mul_f32_e32 v68, 0xbfb8aa3b, v52
	v_mul_f32_e32 v69, 0xbfb8aa3b, v53
	v_exp_f32_e32 v68, v68
	v_exp_f32_e32 v69, v69
	v_add_f32_e32 v68, 1.0, v68
; __device__ __forceinline__ float silu_f(float x) { return x * __builtin_amdgcn_rcpf(1.0f + __expf(-x)); }
; __device__ __forceinline__ u32x4 pack8(const f32x4 a, const f32x4 b) { u32x4 w; w.x = cvt_pk_bf16(a[0], a[1]); w.y = cvt_pk_bf16(a[2], a[3]); w.z = cvt_pk_bf16(b[0], b[1]); w.w = cvt_pk_bf16(b[2], b[3]); return w; }
;     __device__ __forceinline__ void operator()(const f32x4 (&acc)[2][2][4][2], const Unit& u, int wr, int wc, int fr_, int fq_) const {
;     ...
;         for (int ai = 0; ai < 2; ++ai)
; #pragma unroll
;             for (int m = 0; m < 4; ++m) {
;                 const int grow = u.pm * 256 + ai * 128 + m * 16 + wr * 64 + fr;
;                 const float mu = mus[ai * 4 + m], rs = rss[ai * 4 + m];
;                 f32x4 h[2];
; #pragma unroll
;                 for (int n = 0; n < 2; ++n) {
;                     const f32x4 g = (acc[ai][0][m][n] - mu * c1v[0][n]) * rs + c2v[0][n];
;                     const f32x4 up = (acc[ai][1][m][n] - mu * c1v[1][n]) * rs + c2v[1][n];
; #pragma unroll
;                     for (int j = 0; j < 4; ++j) h[n][j] = silu_f(g[j]) * up[j];
;                 }
;                 *(u32x4*)(H + (size_t)grow * KF2 + u.pn * 128 + lc) = pack8(h[0], h[1]);
;             }
	v_add_f32_e32 v69, 1.0, v69
	v_rcp_f32_e32 v68, v68
	v_rcp_f32_e32 v69, v69
	s_nop 0
	v_pk_mul_f32 v[52:53], v[52:53], v[68:69]
	s_nop 0
	v_pk_mul_f32 v[52:53], v[48:49], v[52:53]
	v_pk_fma_f32 v[48:49], v[74:75], v[180:181], v[54:55] op_sel:[0,1,0] neg_lo:[1,0,0] neg_hi:[1,0,0]
	s_nop 0
	v_pk_fma_f32 v[48:49], v[48:49], v[186:187], v[78:79] op_sel_hi:[1,0,1]
	s_nop 0
	v_mul_f32_e32 v54, 0xbfb8aa3b, v48
	v_mul_f32_e32 v55, 0xbfb8aa3b, v49
	v_exp_f32_e32 v54, v54
	v_exp_f32_e32 v55, v55
	v_add_f32_e32 v54, 1.0, v54
	v_add_f32_e32 v55, 1.0, v55
	v_rcp_f32_e32 v54, v54
	v_rcp_f32_e32 v55, v55
	s_nop 0
	v_pk_mul_f32 v[48:49], v[48:49], v[54:55]
	s_nop 0
	v_pk_mul_f32 v[54:55], v[50:51], v[48:49]
	v_cvt_pk_bf16_f32 v50, v52, v53
	v_mad_i64_i32 v[52:53], s[14:15], v178, s1, v[144:145]
	v_lshl_add_u64 v[52:53], v[52:53], 0, s[10:11]
	v_cvt_pk_bf16_f32 v48, v56, v57
	v_cvt_pk_bf16_f32 v49, v58, v59
	v_cvt_pk_bf16_f32 v51, v54, v55
	v_lshl_add_u64 v[52:53], v[52:53], 0, v[146:147]
	global_store_dwordx4 v[52:53], v[48:51], off
	s_nop 1
	v_mul_f32_e32 v48, 0xbfb8aa3b, v44
	v_mul_f32_e32 v49, 0xbfb8aa3b, v45
	v_exp_f32_e32 v48, v48
	v_exp_f32_e32 v49, v49
	v_add_f32_e32 v48, 1.0, v48
	v_add_f32_e32 v49, 1.0, v49
	v_rcp_f32_e32 v48, v48
	v_rcp_f32_e32 v49, v49
	s_nop 0
	v_pk_mul_f32 v[44:45], v[44:45], v[48:49]
	s_nop 0
	v_pk_mul_f32 v[40:41], v[40:41], v[44:45]
	v_pk_fma_f32 v[44:45], v[94:95], v[218:219], v[46:47] op_sel:[0,1,0] neg_lo:[1,0,0] neg_hi:[1,0,0]
	s_nop 0
	v_pk_fma_f32 v[44:45], v[44:45], v[222:223], v[98:99] op_sel_hi:[1,0,1]
	s_nop 0
	v_mul_f32_e32 v46, 0xbfb8aa3b, v44
	v_mul_f32_e32 v47, 0xbfb8aa3b, v45
	v_exp_f32_e32 v46, v46
	v_exp_f32_e32 v47, v47
	v_add_f32_e32 v46, 1.0, v46
	v_add_f32_e32 v47, 1.0, v47
	v_rcp_f32_e32 v46, v46
	v_rcp_f32_e32 v47, v47
	s_nop 0
	v_pk_mul_f32 v[44:45], v[44:45], v[46:47]
	s_nop 0
	v_pk_mul_f32 v[42:43], v[42:43], v[44:45]
	v_mul_f32_e32 v44, 0xbfb8aa3b, v36
	v_mul_f32_e32 v45, 0xbfb8aa3b, v37
	v_exp_f32_e32 v44, v44
	v_exp_f32_e32 v45, v45
	v_add_f32_e32 v44, 1.0, v44
	v_add_f32_e32 v45, 1.0, v45
	v_rcp_f32_e32 v44, v44
	v_rcp_f32_e32 v45, v45
	s_nop 0
	v_pk_mul_f32 v[36:37], v[36:37], v[44:45]
	s_nop 0
	v_pk_mul_f32 v[36:37], v[32:33], v[36:37]
	v_pk_fma_f32 v[32:33], v[74:75], v[218:219], v[38:39] op_sel:[0,1,0] neg_lo:[1,0,0] neg_hi:[1,0,0]
	s_nop 0
	v_pk_fma_f32 v[32:33], v[32:33], v[222:223], v[78:79] op_sel_hi:[1,0,1]
	s_nop 0
	v_mul_f32_e32 v38, 0xbfb8aa3b, v32
	v_mul_f32_e32 v39, 0xbfb8aa3b, v33
	v_exp_f32_e32 v38, v38
	v_exp_f32_e32 v39, v39
	v_add_f32_e32 v38, 1.0, v38
	v_add_f32_e32 v39, 1.0, v39
	v_rcp_f32_e32 v38, v38
	v_rcp_f32_e32 v39, v39
	s_nop 0
	v_pk_mul_f32 v[32:33], v[32:33], v[38:39]
	s_nop 0
	v_pk_mul_f32 v[38:39], v[34:35], v[32:33]
	v_cvt_pk_bf16_f32 v34, v36, v37
	v_mad_i64_i32 v[36:37], s[14:15], v208, s1, v[144:145]
	v_lshl_add_u64 v[36:37], v[36:37], 0, s[10:11]
	v_cvt_pk_bf16_f32 v32, v40, v41
	v_cvt_pk_bf16_f32 v33, v42, v43
	v_cvt_pk_bf16_f32 v35, v38, v39
	v_lshl_add_u64 v[36:37], v[36:37], 0, v[146:147]
	global_store_dwordx4 v[36:37], v[32:35], off
	s_nop 1
	v_mul_f32_e32 v32, 0xbfb8aa3b, v28
	v_mul_f32_e32 v33, 0xbfb8aa3b, v29
	v_exp_f32_e32 v32, v32
	v_exp_f32_e32 v33, v33
	v_add_f32_e32 v32, 1.0, v32
	v_add_f32_e32 v33, 1.0, v33
	v_rcp_f32_e32 v32, v32
	v_rcp_f32_e32 v33, v33
	s_nop 0
	v_pk_mul_f32 v[28:29], v[28:29], v[32:33]
	s_nop 0
	v_pk_mul_f32 v[24:25], v[24:25], v[28:29]
	v_pk_fma_f32 v[28:29], v[94:95], v[220:221], v[30:31] op_sel:[0,1,0] neg_lo:[1,0,0] neg_hi:[1,0,0]
	s_nop 0
	v_pk_fma_f32 v[28:29], v[28:29], v[224:225], v[98:99] op_sel_hi:[1,0,1]
	s_nop 0
	v_mul_f32_e32 v30, 0xbfb8aa3b, v28
; __device__ __forceinline__ float silu_f(float x) { return x * __builtin_amdgcn_rcpf(1.0f + __expf(-x)); }
; #define PG8_WAIT_V(n) asm volatile("s_waitcnt vmcnt(" #n ")" ::: "memory")
; #define PG8_BAR __builtin_amdgcn_s_barrier()
; __device__ __forceinline__ u32x4 pack8(const f32x4 a, const f32x4 b) { u32x4 w; w.x = cvt_pk_bf16(a[0], a[1]); w.y = cvt_pk_bf16(a[2], a[3]); w.z = cvt_pk_bf16(b[0], b[1]); w.w = cvt_pk_bf16(b[2], b[3]); return w; }
; template <class Epi>
; __device__ __forceinline__ void gemm_phase(LAS unsigned char* lds, const Gemm g, const StaticOrder& S, const Epi& E) {
;     ...
;         if (!has_next) break;
; #pragma unroll
;         for (int a = 0; a < 2; ++a)
; #pragma unroll
;             for (int b = 0; b < 2; ++b)
; #pragma unroll
;                 for (int m = 0; m < 4; ++m)
; #pragma unroll
;                     for (int n = 0; n < 2; ++n) acc[a][b][m][n] = (f32x4){0.f, 0.f, 0.f, 0.f};
;         cur = nxt; cA = nA; cB = nB; ++ui;
;     }
;     PG8_WAIT_V(0);
;     if (wr == 0) PG8_BAR;
;     __device__ __forceinline__ void operator()(const f32x4 (&acc)[2][2][4][2], const Unit& u, int wr, int wc, int fr_, int fq_) const {
;     ...
;         for (int ai = 0; ai < 2; ++ai)
; #pragma unroll
;             for (int m = 0; m < 4; ++m) {
;                 const int grow = u.pm * 256 + ai * 128 + m * 16 + wr * 64 + fr;
;                 const float mu = mus[ai * 4 + m], rs = rss[ai * 4 + m];
;                 f32x4 h[2];
; #pragma unroll
;                 for (int n = 0; n < 2; ++n) {
;                     const f32x4 g = (acc[ai][0][m][n] - mu * c1v[0][n]) * rs + c2v[0][n];
;                     const f32x4 up = (acc[ai][1][m][n] - mu * c1v[1][n]) * rs + c2v[1][n];
; #pragma unroll
;                     for (int j = 0; j < 4; ++j) h[n][j] = silu_f(g[j]) * up[j];
;                 }
;                 *(u32x4*)(H + (size_t)grow * KF2 + u.pn * 128 + lc) = pack8(h[0], h[1]);
;             }
	v_mul_f32_e32 v31, 0xbfb8aa3b, v29
	v_exp_f32_e32 v30, v30
	v_exp_f32_e32 v31, v31
	v_add_f32_e32 v30, 1.0, v30
	v_add_f32_e32 v31, 1.0, v31
	v_rcp_f32_e32 v30, v30
	v_rcp_f32_e32 v31, v31
	s_nop 0
	v_pk_mul_f32 v[28:29], v[28:29], v[30:31]
	s_nop 0
	v_pk_mul_f32 v[26:27], v[26:27], v[28:29]
	v_mul_f32_e32 v28, 0xbfb8aa3b, v20
	v_mul_f32_e32 v29, 0xbfb8aa3b, v21
	v_exp_f32_e32 v28, v28
	v_exp_f32_e32 v29, v29
	v_add_f32_e32 v28, 1.0, v28
	v_add_f32_e32 v29, 1.0, v29
	v_rcp_f32_e32 v28, v28
	v_rcp_f32_e32 v29, v29
	s_nop 0
	v_pk_mul_f32 v[20:21], v[20:21], v[28:29]
	s_nop 0
	v_pk_mul_f32 v[20:21], v[16:17], v[20:21]
	v_pk_fma_f32 v[16:17], v[74:75], v[220:221], v[22:23] op_sel:[0,1,0] neg_lo:[1,0,0] neg_hi:[1,0,0]
	s_nop 0
	v_pk_fma_f32 v[16:17], v[16:17], v[224:225], v[78:79] op_sel_hi:[1,0,1]
	s_nop 0
	v_mul_f32_e32 v22, 0xbfb8aa3b, v16
	v_mul_f32_e32 v23, 0xbfb8aa3b, v17
	v_exp_f32_e32 v22, v22
	v_exp_f32_e32 v23, v23
	v_add_f32_e32 v22, 1.0, v22
	v_add_f32_e32 v23, 1.0, v23
	v_rcp_f32_e32 v22, v22
	v_rcp_f32_e32 v23, v23
	s_nop 0
	v_pk_mul_f32 v[16:17], v[16:17], v[22:23]
	s_nop 0
	v_pk_mul_f32 v[22:23], v[18:19], v[16:17]
	v_cvt_pk_bf16_f32 v18, v20, v21
	v_mad_i64_i32 v[20:21], s[14:15], v212, s1, v[144:145]
	v_lshl_add_u64 v[20:21], v[20:21], 0, s[10:11]
	v_cvt_pk_bf16_f32 v16, v24, v25
	v_cvt_pk_bf16_f32 v17, v26, v27
	v_cvt_pk_bf16_f32 v19, v22, v23
	v_lshl_add_u64 v[20:21], v[20:21], 0, v[146:147]
	global_store_dwordx4 v[20:21], v[16:19], off
	s_nop 1
	v_mul_f32_e32 v16, 0xbfb8aa3b, v12
	v_mul_f32_e32 v17, 0xbfb8aa3b, v13
	v_exp_f32_e32 v16, v16
	v_exp_f32_e32 v17, v17
	v_add_f32_e32 v16, 1.0, v16
	v_add_f32_e32 v17, 1.0, v17
	v_rcp_f32_e32 v16, v16
	v_rcp_f32_e32 v17, v17
	s_nop 0
	v_pk_mul_f32 v[12:13], v[12:13], v[16:17]
	s_nop 0
	v_pk_mul_f32 v[8:9], v[8:9], v[12:13]
	v_pk_fma_f32 v[12:13], v[94:95], v[160:161], v[14:15] op_sel:[0,1,0] neg_lo:[1,0,0] neg_hi:[1,0,0]
	s_nop 0
	v_pk_fma_f32 v[12:13], v[12:13], v[162:163], v[98:99] op_sel_hi:[1,0,1]
	s_nop 0
	v_mul_f32_e32 v14, 0xbfb8aa3b, v12
	v_mul_f32_e32 v15, 0xbfb8aa3b, v13
	v_exp_f32_e32 v14, v14
	v_exp_f32_e32 v15, v15
	v_add_f32_e32 v14, 1.0, v14
	v_add_f32_e32 v15, 1.0, v15
	v_rcp_f32_e32 v14, v14
	v_rcp_f32_e32 v15, v15
	s_nop 0
	v_pk_mul_f32 v[12:13], v[12:13], v[14:15]
	s_nop 0
	v_pk_mul_f32 v[10:11], v[10:11], v[12:13]
	v_mul_f32_e32 v12, 0xbfb8aa3b, v4
	v_mul_f32_e32 v13, 0xbfb8aa3b, v5
	v_exp_f32_e32 v12, v12
	v_exp_f32_e32 v13, v13
	v_add_f32_e32 v12, 1.0, v12
	v_add_f32_e32 v13, 1.0, v13
	v_rcp_f32_e32 v12, v12
	v_rcp_f32_e32 v13, v13
	s_nop 0
	v_pk_mul_f32 v[4:5], v[4:5], v[12:13]
	s_nop 0
	v_pk_mul_f32 v[4:5], v[0:1], v[4:5]
	v_pk_fma_f32 v[0:1], v[74:75], v[160:161], v[6:7] op_sel:[0,1,0] neg_lo:[1,0,0] neg_hi:[1,0,0]
	s_nop 0
	v_pk_fma_f32 v[0:1], v[0:1], v[162:163], v[78:79] op_sel_hi:[1,0,1]
	s_nop 0
	v_mul_f32_e32 v6, 0xbfb8aa3b, v0
	v_mul_f32_e32 v7, 0xbfb8aa3b, v1
	v_exp_f32_e32 v6, v6
	v_exp_f32_e32 v7, v7
	v_add_f32_e32 v6, 1.0, v6
	v_add_f32_e32 v7, 1.0, v7
	v_rcp_f32_e32 v6, v6
	v_rcp_f32_e32 v7, v7
	s_nop 0
	v_pk_mul_f32 v[0:1], v[0:1], v[6:7]
	s_nop 0
	v_pk_mul_f32 v[6:7], v[2:3], v[0:1]
	v_cvt_pk_bf16_f32 v2, v4, v5
	v_mad_i64_i32 v[4:5], s[14:15], v206, s1, v[144:145]
	v_lshl_add_u64 v[4:5], v[4:5], 0, s[10:11]
	v_cvt_pk_bf16_f32 v0, v8, v9
	v_cvt_pk_bf16_f32 v1, v10, v11
	v_cvt_pk_bf16_f32 v3, v6, v7
	v_lshl_add_u64 v[4:5], v[4:5], 0, v[146:147]
	s_mov_b64 s[14:15], s[44:45]
	s_mov_b64 s[10:11], s[42:43]
	global_store_dwordx4 v[4:5], v[0:3], off
	s_cbranch_vccz .LBB0_875
	s_waitcnt vmcnt(0)
	s_cmpk_gt_u32 s18, 0xff
	s_cbranch_scc1 .LBB0_882
	s_barrier
